# speedup vs baseline: 1.3272x; 1.3272x over previous
; __device__ __forceinline__ void preproc_phase(Frame& F, int layer, int b, int cu_lo, int ncu) {
;     ...
;             const int L_ = opaque_int(layer);
;             const float* cw = INP(I_M_CONV_W) + L_ * 4 * D; const float* cb = INP(I_M_CONV_B) + L_ * D;
;             const float* wq = INP(I_M_WQ) + L_ * 256 * 16; const float* wk = INP(I_M_WK) + L_ * 256 * 16; const float* wv = INP(I_M_WV) + L_ * 256 * 16;
;             const float* wi = INP(I_M_W_I) + (size_t)L_ * 3072 * 4; const float* wf = INP(I_M_W_F) + (size_t)L_ * 3072 * 4;
;             bf16_t* MQ = WSP(bf16_t, OFF_MQ); bf16_t* MK = WSP(bf16_t, OFF_MK); bf16_t* MV = WSP(bf16_t, OFF_MV); bf16_t* XC = WSP(bf16_t, OFF_XC);
;             float xm[7][4];
; #pragma unroll
;             for (int r = 0; r < 7; ++r) { const int t = t0 - 3 + r;
;                 if (t >= 0) { const u32x2 w = *(const u32x2*)(proj + (size_t)t * NP + C_MX + cc); xm[r][0] = bflo(w.x); xm[r][1] = bfhi(w.x); xm[r][2] = bflo(w.y); xm[r][3] = bfhi(w.y); }
;                 else { xm[r][0] = xm[r][1] = xm[r][2] = xm[r][3] = 0.f; } }
;             const f32x4 cbv = *(const f32x4*)(cb + cc); f32x4 cwv[4];
; #pragma unroll
;             for (int j = 0; j < 4; ++j) cwv[j] = *(const f32x4*)(cw + j * D + cc);
;             float xc[4][4], q[4][4], k[4][4], v[4][4];
; #pragma unroll
;             for (int a = 0; a < 4; ++a)
; #pragma unroll
;                 for (int c = 0; c < 4; ++c) { float s = cbv[c];
; #pragma unroll
;                     for (int j = 0; j < 4; ++j) s += cwv[j][c] * xm[a + j][c];
;                     xc[a][c] = siluf_(s); }
;             const int nb = cc >> 2;
;             {   f32x4 w[4];
; #pragma unroll
;                 for (int c = 0; c < 4; ++c) w[c] = *(const f32x4*)(wq + nb * 16 + c * 4);
; #pragma unroll
;                 for (int a = 0; a < 4; ++a)
; #pragma unroll
;                     for (int d = 0; d < 4; ++d) q[a][d] = xc[a][0] * w[0][d] + xc[a][1] * w[1][d] + xc[a][2] * w[2][d] + xc[a][3] * w[3][d];
; #pragma unroll
;                 for (int c = 0; c < 4; ++c) w[c] = *(const f32x4*)(wk + nb * 16 + c * 4);
; #pragma unroll
;                 for (int a = 0; a < 4; ++a)
; #pragma unroll
;                     for (int d = 0; d < 4; ++d) k[a][d] = xc[a][0] * w[0][d] + xc[a][1] * w[1][d] + xc[a][2] * w[2][d] + xc[a][3] * w[3][d];
; #pragma unroll
.LBB0_298:
	s_lshl_b32 s4, s0, 12
	s_ashr_i32 s5, s4, 31
	s_lshl_b64 s[10:11], s[4:5], 2
	s_waitcnt lgkmcnt(0)
	v_lshl_add_u64 v[2:3], v[2:3], 0, s[10:11]
	v_lshl_add_u64 v[2:3], v[2:3], 0, v[122:123]
	s_movk_i32 s1, 0x1000
	v_add_co_u32_e32 v16, vcc, s1, v2
	s_mul_hi_i32 s5, s0, 0xc000
	s_nop 0
	v_addc_co_u32_e32 v17, vcc, 0, v3, vcc
	flat_load_dwordx4 v[170:173], v[2:3]
	flat_load_dwordx4 v[54:57], v[16:17]
	v_add_co_u32_e32 v16, vcc, s3, v2
	s_mul_i32 s4, s0, 0xc000
	s_nop 0
	v_addc_co_u32_e32 v17, vcc, 0, v3, vcc
	v_add_co_u32_e32 v2, vcc, s89, v2
	v_lshl_add_u64 v[70:71], v[14:15], 0, s[4:5]
	s_nop 0
	v_addc_co_u32_e32 v3, vcc, 0, v3, vcc
	flat_load_dwordx4 v[174:177], v[16:17]
	flat_load_dwordx4 v[58:61], v[2:3]
	v_lshl_add_u64 v[2:3], v[6:7], 0, s[10:11]
	v_lshl_add_u64 v[2:3], v[2:3], 0, v[88:89]
	v_lshl_add_u64 v[2:3], v[2:3], 0, s[96:97]
	s_lshl_b32 vcc_lo, s0, 10
	flat_load_dwordx4 v[18:21], v[2:3]
	flat_load_dwordx4 v[22:25], v[2:3] offset:16
	flat_load_dwordx4 v[26:29], v[2:3] offset:32
	flat_load_dwordx4 v[30:33], v[2:3] offset:48
	v_lshl_add_u64 v[2:3], v[8:9], 0, s[10:11]
	s_ashr_i32 vcc_hi, vcc_lo, 31
	v_lshl_add_u64 v[2:3], v[2:3], 0, v[88:89]
	s_lshl_b64 s[0:1], vcc, 2
	v_lshl_add_u64 v[14:15], v[2:3], 0, s[96:97]
	v_lshl_add_u64 v[16:17], v[10:11], 0, s[10:11]
	v_lshl_add_u64 v[72:73], v[12:13], 0, s[4:5]
	v_lshl_add_u64 v[12:13], v[4:5], 0, s[0:1]
	flat_load_dwordx4 v[2:5], v[14:15]
	flat_load_dwordx4 v[6:9], v[14:15] offset:16
	v_lshl_add_u64 v[38:39], v[16:17], 0, v[88:89]
	v_lshl_add_u64 v[34:35], v[12:13], 0, v[122:123]
	flat_load_dwordx4 v[10:13], v[14:15] offset:32
	v_lshl_add_u64 v[46:47], v[38:39], 0, s[96:97]
	flat_load_dwordx4 v[14:17], v[14:15] offset:48
	s_nop 0
	flat_load_dwordx4 v[34:37], v[34:35]
	s_nop 0
	flat_load_dwordx4 v[38:41], v[46:47]
	flat_load_dwordx4 v[50:53], v[46:47] offset:16
	flat_load_dwordx4 v[42:45], v[46:47] offset:32
	s_nop 0
	flat_load_dwordx4 v[46:49], v[46:47] offset:48
	s_mov_b64 s[0:1], 0x400
	v_lshl_add_u64 v[122:123], v[122:123], 0, s[0:1]
	s_waitcnt vmcnt(0) lgkmcnt(0)
	v_lshlrev_b32_e32 v148, 16, v190
	v_and_b32_e32 v144, 0xffff0000, v190
	v_lshlrev_b32_e32 v138, 16, v191
	v_and_b32_e32 v136, 0xffff0000, v191
	v_lshlrev_b32_e32 v149, 16, v192
	v_and_b32_e32 v145, 0xffff0000, v192
	v_lshlrev_b32_e32 v139, 16, v193
	v_and_b32_e32 v137, 0xffff0000, v193
	v_lshlrev_b32_e32 v124, 16, v194
	v_and_b32_e32 v130, 0xffff0000, v194
	v_lshlrev_b32_e32 v128, 16, v195
	v_and_b32_e32 v126, 0xffff0000, v195
	v_lshlrev_b32_e32 v125, 16, v196
	v_and_b32_e32 v131, 0xffff0000, v196
	v_lshlrev_b32_e32 v129, 16, v197
	v_and_b32_e32 v127, 0xffff0000, v197
	v_lshlrev_b32_e32 v133, 16, v198
	v_and_b32_e32 v143, 0xffff0000, v198
	v_lshlrev_b32_e32 v141, 16, v199
	v_and_b32_e32 v135, 0xffff0000, v199
	v_lshlrev_b32_e32 v79, 16, v200
	v_and_b32_e32 v81, 0xffff0000, v200
	v_lshlrev_b32_e32 v77, 16, v201
	v_and_b32_e32 v75, 0xffff0000, v201
	v_lshlrev_b32_e32 v63, 16, v202
	v_and_b32_e32 v69, 0xffff0000, v202
	v_lshlrev_b32_e32 v67, 16, v203
	v_and_b32_e32 v65, 0xffff0000, v203
	v_mov_b32_e32 v132, v125
	v_mov_b32_e32 v178, v145
	v_mov_b32_e32 v179, v130
	v_mov_b32_e32 v142, v131
	v_mov_b32_e32 v180, v139
	v_mov_b32_e32 v181, v128
	v_mov_b32_e32 v140, v129
	v_mov_b32_e32 v182, v137
	v_mov_b32_e32 v183, v126
	v_mov_b32_e32 v134, v127
	v_mov_b32_e32 v78, v133
	v_mov_b32_e32 v62, v79
	v_mov_b32_e32 v166, v149
	v_mov_b32_e32 v80, v143
	v_mov_b32_e32 v68, v81
	v_mov_b32_e32 v167, v124
	v_mov_b32_e32 v74, v135
	v_mov_b32_e32 v64, v75
	v_mov_b32_e32 v76, v141
	v_mov_b32_e32 v66, v77
	v_mov_b32_e32 v184, v170
	v_mov_b32_e32 v188, v172
	v_mov_b32_e32 v185, v54
	v_mov_b32_e32 v54, v171
	v_mov_b32_e32 v189, v56
	v_mov_b32_e32 v56, v173
	v_pk_mul_f32 v[222:223], v[148:149], v[184:185]
	v_pk_mul_f32 v[216:217], v[144:145], v[54:55]
	v_pk_mul_f32 v[242:243], v[138:139], v[188:189]
	v_pk_mul_f32 v[138:139], v[136:137], v[56:57]
	v_pk_mul_f32 v[148:149], v[178:179], v[54:55]
	v_mov_b32_e32 v186, v174
	v_mov_b32_e32 v187, v58
	v_mov_b32_e32 v58, v175
	v_pk_mul_f32 v[218:219], v[124:125], v[186:187]
	v_pk_mul_f32 v[170:171], v[132:133], v[186:187]
	v_pk_mul_f32 v[208:209], v[180:181], v[188:189]
	v_pk_mul_f32 v[212:213], v[182:183], v[56:57]
	v_pk_mul_f32 v[190:191], v[78:79], v[186:187]
	v_pk_mul_f32 v[180:181], v[130:131], v[54:55]
	v_pk_mul_f32 v[204:205], v[128:129], v[188:189]
	v_pk_mul_f32 v[182:183], v[126:127], v[56:57]
	v_pk_mul_f32 v[194:195], v[62:63], v[186:187]
	v_pk_mul_f32 v[186:187], v[142:143], v[54:55]
	v_pk_mul_f32 v[200:201], v[140:141], v[188:189]
	v_pk_mul_f32 v[188:189], v[134:135], v[56:57]
	v_mov_b32_e32 v54, v18
	v_mov_b32_e32 v56, v22
	v_mov_b32_e32 v57, v24
	v_mov_b32_e32 v24, v23
	v_mov_b32_e32 v18, v2
	v_mov_b32_e32 v22, v6
	v_mov_b32_e32 v23, v8
	v_mov_b32_e32 v8, v7
	v_mov_b32_e32 v2, v38
	v_mov_b32_e32 v38, v131
	v_mov_b32_e32 v6, v50
	v_mov_b32_e32 v7, v52
	v_mov_b32_e32 v197, v60
	v_mov_b32_e32 v60, v177
	v_pk_mul_f32 v[214:215], v[130:131], v[58:59]
	v_pk_mul_f32 v[144:145], v[142:143], v[58:59]
	v_pk_mul_f32 v[174:175], v[80:81], v[58:59]
	v_pk_mul_f32 v[178:179], v[68:69], v[58:59]
	v_mov_b32_e32 v55, v20
	v_mov_b32_e32 v58, v26
	v_mov_b32_e32 v59, v28
	v_mov_b32_e32 v20, v19
	v_mov_b32_e32 v28, v27
	v_mov_b32_e32 v19, v4
	v_mov_b32_e32 v26, v10
	v_mov_b32_e32 v27, v12
	v_mov_b32_e32 v4, v3
	v_mov_b32_e32 v12, v11
	v_mov_b32_e32 v62, v125
	v_mov_b32_e32 v3, v40
	v_pk_mul_f32 v[10:11], v[38:39], v[6:7] op_sel_hi:[0,1]
	v_mov_b32_e32 v52, v51
	v_mov_b32_e32 v196, v176
	v_pk_mul_f32 v[136:137], v[126:127], v[60:61]
	v_pk_mul_f32 v[206:207], v[166:167], v[184:185]
; __device__ __forceinline__ unsigned pk2(float lo, float hi) { return f2bf(lo) | (f2bf(hi) << 16); }
; __device__ __forceinline__ void preproc_phase(Frame& F, int layer, int b, int cu_lo, int ncu) {
;     ...
;             const f32x4 cbv = *(const f32x4*)(cb + cc); f32x4 cwv[4];
; #pragma unroll
;             for (int j = 0; j < 4; ++j) cwv[j] = *(const f32x4*)(cw + j * D + cc);
;             float xc[4][4], q[4][4], k[4][4], v[4][4];
; #pragma unroll
;             for (int a = 0; a < 4; ++a)
; #pragma unroll
;                 for (int c = 0; c < 4; ++c) { float s = cbv[c];
; #pragma unroll
;                     for (int j = 0; j < 4; ++j) s += cwv[j][c] * xm[a + j][c];
;                     xc[a][c] = siluf_(s); }
;             const int nb = cc >> 2;
;             {   f32x4 w[4];
; #pragma unroll
;                 for (int c = 0; c < 4; ++c) w[c] = *(const f32x4*)(wq + nb * 16 + c * 4);
; #pragma unroll
;                 for (int a = 0; a < 4; ++a)
; #pragma unroll
;                     for (int d = 0; d < 4; ++d) q[a][d] = xc[a][0] * w[0][d] + xc[a][1] * w[1][d] + xc[a][2] * w[2][d] + xc[a][3] * w[3][d];
; #pragma unroll
;                 for (int c = 0; c < 4; ++c) w[c] = *(const f32x4*)(wk + nb * 16 + c * 4);
; #pragma unroll
;                 for (int a = 0; a < 4; ++a)
; #pragma unroll
;                     for (int d = 0; d < 4; ++d) k[a][d] = xc[a][0] * w[0][d] + xc[a][1] * w[1][d] + xc[a][2] * w[2][d] + xc[a][3] * w[3][d];
; #pragma unroll
;                 for (int c = 0; c < 4; ++c) w[c] = *(const f32x4*)(wv + nb * 16 + c * 4);
; #pragma unroll
;                 for (int a = 0; a < 4; ++a)
; #pragma unroll
;                     for (int d = 0; d < 4; ++d) v[a][d] = xm[a + 3][0] * w[0][d] + xm[a + 3][1] * w[1][d] + xm[a + 3][2] * w[2][d] + xm[a + 3][3] * w[3][d];
;             }
; #pragma unroll
;             for (int a = 0; a < 4; ++a) { const size_t o = (size_t)(t0 + a) * D + cc; u32x2 w;
;                 w.x = pk2(q[a][0], q[a][1]); w.y = pk2(q[a][2], q[a][3]); *(u32x2*)(MQ + o) = w;
;                 w.x = pk2(k[a][0], k[a][1]); w.y = pk2(k[a][2], k[a][3]); *(u32x2*)(MK + o) = w;
;                 w.x = pk2(v[a][0], v[a][1]); w.y = pk2(v[a][2], v[a][3]); *(u32x2*)(MV + o) = w;
;                 w.x = pk2(xc[a][0], xc[a][1]); w.y = pk2(xc[a][2], xc[a][3]); *(u32x2*)(XC + o) = w; }
	v_pk_mul_f32 v[210:211], v[134:135], v[60:61]
	v_pk_mul_f32 v[202:203], v[124:125], v[184:185]
	v_pk_mul_f32 v[176:177], v[74:75], v[60:61]
	v_pk_mul_f32 v[198:199], v[132:133], v[184:185]
	v_pk_mul_f32 v[184:185], v[64:65], v[60:61]
	v_mov_b32_e32 v60, v30
	v_mov_b32_e32 v61, v32
	v_mov_b32_e32 v32, v31
	v_mov_b32_e32 v30, v14
	v_mov_b32_e32 v31, v16
	v_mov_b32_e32 v16, v15
	v_pk_fma_f32 v[14:15], v[62:63], v[2:3], v[10:11] op_sel_hi:[0,1,1]
	v_mov_b32_e32 v50, v129
	v_mov_b32_e32 v10, v42
	v_mov_b32_e32 v11, v44
	v_mov_b32_e32 v40, v39
	v_pk_mul_f32 v[38:39], v[38:39], v[52:53] op_sel_hi:[0,1]
	v_pk_fma_f32 v[124:125], v[50:51], v[10:11], v[14:15] op_sel_hi:[0,1,1]
	v_mov_b32_e32 v42, v127
	v_mov_b32_e32 v14, v46
	v_mov_b32_e32 v15, v48
	v_pk_fma_f32 v[38:39], v[62:63], v[40:41], v[38:39] op_sel_hi:[0,1,1]
	v_mov_b32_e32 v44, v43
	v_pk_fma_f32 v[124:125], v[42:43], v[14:15], v[124:125] op_sel_hi:[0,1,1]
	v_pk_fma_f32 v[38:39], v[50:51], v[44:45], v[38:39] op_sel_hi:[0,1,1]
	v_mov_b32_e32 v48, v47
	v_pk_fma_f32 v[126:127], v[42:43], v[48:49], v[38:39] op_sel_hi:[0,1,1]
	v_and_b32_sdwa v39, v124, v224 dst_sel:DWORD dst_unused:UNUSED_PAD src0_sel:WORD_1 src1_sel:DWORD
	v_add3_u32 v42, v124, v39, s81
	v_and_b32_sdwa v39, v127, v224 dst_sel:DWORD dst_unused:UNUSED_PAD src0_sel:WORD_1 src1_sel:DWORD
	v_and_b32_sdwa v38, v125, v224 dst_sel:DWORD dst_unused:UNUSED_PAD src0_sel:WORD_1 src1_sel:DWORD
	v_and_b32_sdwa v43, v126, v224 dst_sel:DWORD dst_unused:UNUSED_PAD src0_sel:WORD_1 src1_sel:DWORD
	v_add3_u32 v39, v127, v39, s81
	v_add3_u32 v38, v125, v38, s81
	v_add3_u32 v43, v126, v43, s81
	v_and_b32_e32 v39, 0xffff0000, v39
	v_and_b32_e32 v62, 0xffff0000, v43
	v_or_b32_sdwa v43, v39, v38 dst_sel:DWORD dst_unused:UNUSED_PAD src0_sel:DWORD src1_sel:WORD_1
	v_mov_b32_e32 v38, v34
	v_mov_b32_e32 v39, v36
	v_mov_b32_e32 v46, v222
	v_mov_b32_e32 v47, v242
	v_pk_mul_f32 v[220:221], v[128:129], v[196:197]
	v_pk_add_f32 v[46:47], v[38:39], v[46:47]
	v_mov_b32_e32 v242, v223
	v_pk_add_f32 v[46:47], v[46:47], v[242:243]
	v_mov_b32_e32 v50, v218
	v_mov_b32_e32 v51, v220
	v_pk_add_f32 v[46:47], v[46:47], v[50:51]
	v_mov_b32_e32 v220, v219
	v_pk_add_f32 v[46:47], v[46:47], v[220:221]
	v_mov_b32_e32 v36, v35
	v_mul_f32_e32 v34, 0xbfb8aa3b, v46
	v_exp_f32_e32 v64, v34
	v_mov_b32_e32 v34, v216
	v_mov_b32_e32 v35, v138
	v_pk_add_f32 v[34:35], v[36:37], v[34:35]
	v_mov_b32_e32 v138, v217
	v_pk_add_f32 v[34:35], v[34:35], v[138:139]
	v_mov_b32_e32 v50, v214
	v_mov_b32_e32 v51, v136
	v_pk_add_f32 v[34:35], v[34:35], v[50:51]
	v_mov_b32_e32 v136, v215
	v_pk_add_f32 v[34:35], v[34:35], v[136:137]
	v_or_b32_sdwa v42, v62, v42 dst_sel:DWORD dst_unused:UNUSED_PAD src0_sel:DWORD src1_sel:WORD_1
	v_mul_f32_e32 v50, 0xbfb8aa3b, v34
	v_exp_f32_e32 v51, v50
	v_add_f32_e32 v50, 1.0, v64
	v_mul_f32_e32 v62, 0xbfb8aa3b, v47
	v_mul_f32_e32 v64, 0xbfb8aa3b, v35
	v_exp_f32_e32 v62, v62
	v_exp_f32_e32 v64, v64
	v_add_f32_e32 v51, 1.0, v51
	v_rcp_f32_e32 v128, v51
	v_add_f32_e32 v51, 1.0, v62
	v_add_f32_e32 v62, 1.0, v64
	v_rcp_f32_e32 v129, v62
	v_rcp_f32_e32 v50, v50
	v_rcp_f32_e32 v51, v51
	v_lshl_add_u64 v[166:167], s[28:29], 0, v[0:1]
	v_add_co_u32_e32 v130, vcc, s58, v166
	v_pk_mul_f32 v[34:35], v[34:35], v[128:129]
	s_nop 0
	v_addc_co_u32_e32 v131, vcc, 0, v167, vcc
	flat_store_dwordx2 v[130:131], v[42:43]
	v_pk_mul_f32 v[42:43], v[46:47], v[50:51]
	v_pk_mul_f32 v[46:47], v[56:57], v[34:35] op_sel_hi:[1,0]
	v_mov_b32_e32 v62, v141
	v_pk_fma_f32 v[46:47], v[54:55], v[42:43], v[46:47] op_sel_hi:[1,0,1]
	v_mov_b32_e32 v64, v135
	v_pk_fma_f32 v[46:47], v[58:59], v[42:43], v[46:47] op_sel:[0,1,0]
	v_pk_mul_f32 v[172:173], v[140:141], v[196:197]
	v_pk_fma_f32 v[130:131], v[60:61], v[34:35], v[46:47] op_sel:[0,1,0]
	v_pk_mul_f32 v[46:47], v[24:25], v[34:35] op_sel_hi:[1,0]
	v_mov_b32_e32 v140, v144
	v_pk_fma_f32 v[46:47], v[20:21], v[42:43], v[46:47] op_sel_hi:[1,0,1]
	v_mov_b32_e32 v141, v210
	v_pk_fma_f32 v[46:47], v[28:29], v[42:43], v[46:47] op_sel:[0,1,0]
	v_pk_mul_f32 v[192:193], v[76:77], v[196:197]
	v_pk_fma_f32 v[128:129], v[32:33], v[34:35], v[46:47] op_sel:[0,1,0]
	v_and_b32_sdwa v47, v130, v224 dst_sel:DWORD dst_unused:UNUSED_PAD src0_sel:WORD_1 src1_sel:DWORD
	v_add3_u32 v50, v130, v47, s81
	v_and_b32_sdwa v47, v129, v224 dst_sel:DWORD dst_unused:UNUSED_PAD src0_sel:WORD_1 src1_sel:DWORD
	v_and_b32_sdwa v51, v128, v224 dst_sel:DWORD dst_unused:UNUSED_PAD src0_sel:WORD_1 src1_sel:DWORD
	v_and_b32_sdwa v46, v131, v224 dst_sel:DWORD dst_unused:UNUSED_PAD src0_sel:WORD_1 src1_sel:DWORD
	v_add3_u32 v47, v129, v47, s81
	v_add3_u32 v51, v128, v51, s81
	v_add3_u32 v46, v131, v46, s81
	v_and_b32_e32 v47, 0xffff0000, v47
	v_and_b32_e32 v51, 0xffff0000, v51
	v_or_b32_sdwa v47, v47, v46 dst_sel:DWORD dst_unused:UNUSED_PAD src0_sel:DWORD src1_sel:WORD_1
	v_or_b32_sdwa v46, v51, v50 dst_sel:DWORD dst_unused:UNUSED_PAD src0_sel:DWORD src1_sel:WORD_1
	v_add_co_u32_e32 v50, vcc, s57, v166
	v_pk_mul_f32 v[196:197], v[66:67], v[196:197]
	s_nop 0
	v_addc_co_u32_e32 v51, vcc, 0, v167, vcc
	flat_store_dwordx2 v[50:51], v[46:47]
	v_pk_mul_f32 v[46:47], v[22:23], v[34:35] op_sel_hi:[1,0]
	v_mov_b32_e32 v210, v145
	v_pk_fma_f32 v[46:47], v[18:19], v[42:43], v[46:47] op_sel_hi:[1,0,1]
	v_mov_b32_e32 v74, v174
	v_pk_fma_f32 v[46:47], v[26:27], v[42:43], v[46:47] op_sel:[0,1,0]
	s_nop 0
	v_pk_fma_f32 v[138:139], v[34:35], v[30:31], v[46:47] op_sel:[1,0,0]
	v_pk_mul_f32 v[46:47], v[8:9], v[34:35] op_sel_hi:[1,0]
	s_nop 0
	v_pk_fma_f32 v[46:47], v[4:5], v[42:43], v[46:47] op_sel_hi:[1,0,1]
	s_nop 0
	v_pk_fma_f32 v[46:47], v[12:13], v[42:43], v[46:47] op_sel:[0,1,0]
	s_nop 0
; __device__ __forceinline__ unsigned pk2(float lo, float hi) { return f2bf(lo) | (f2bf(hi) << 16); }
; __device__ __forceinline__ void preproc_phase(Frame& F, int layer, int b, int cu_lo, int ncu) {
;     ...
;             const f32x4 cbv = *(const f32x4*)(cb + cc); f32x4 cwv[4];
; #pragma unroll
;             for (int j = 0; j < 4; ++j) cwv[j] = *(const f32x4*)(cw + j * D + cc);
;             float xc[4][4], q[4][4], k[4][4], v[4][4];
; #pragma unroll
;             for (int a = 0; a < 4; ++a)
; #pragma unroll
;                 for (int c = 0; c < 4; ++c) { float s = cbv[c];
; #pragma unroll
;                     for (int j = 0; j < 4; ++j) s += cwv[j][c] * xm[a + j][c];
;                     xc[a][c] = siluf_(s); }
;             const int nb = cc >> 2;
;             {   f32x4 w[4];
; #pragma unroll
;                 for (int c = 0; c < 4; ++c) w[c] = *(const f32x4*)(wq + nb * 16 + c * 4);
; #pragma unroll
;                 for (int a = 0; a < 4; ++a)
; #pragma unroll
;                     for (int d = 0; d < 4; ++d) q[a][d] = xc[a][0] * w[0][d] + xc[a][1] * w[1][d] + xc[a][2] * w[2][d] + xc[a][3] * w[3][d];
; #pragma unroll
;                 for (int c = 0; c < 4; ++c) w[c] = *(const f32x4*)(wk + nb * 16 + c * 4);
; #pragma unroll
;                 for (int a = 0; a < 4; ++a)
; #pragma unroll
;                     for (int d = 0; d < 4; ++d) k[a][d] = xc[a][0] * w[0][d] + xc[a][1] * w[1][d] + xc[a][2] * w[2][d] + xc[a][3] * w[3][d];
; #pragma unroll
;                 for (int c = 0; c < 4; ++c) w[c] = *(const f32x4*)(wv + nb * 16 + c * 4);
; #pragma unroll
;                 for (int a = 0; a < 4; ++a)
; #pragma unroll
;                     for (int d = 0; d < 4; ++d) v[a][d] = xm[a + 3][0] * w[0][d] + xm[a + 3][1] * w[1][d] + xm[a + 3][2] * w[2][d] + xm[a + 3][3] * w[3][d];
;             }
; #pragma unroll
;             for (int a = 0; a < 4; ++a) { const size_t o = (size_t)(t0 + a) * D + cc; u32x2 w;
;                 w.x = pk2(q[a][0], q[a][1]); w.y = pk2(q[a][2], q[a][3]); *(u32x2*)(MQ + o) = w;
;                 w.x = pk2(k[a][0], k[a][1]); w.y = pk2(k[a][2], k[a][3]); *(u32x2*)(MK + o) = w;
;                 w.x = pk2(v[a][0], v[a][1]); w.y = pk2(v[a][2], v[a][3]); *(u32x2*)(MV + o) = w;
;                 w.x = pk2(xc[a][0], xc[a][1]); w.y = pk2(xc[a][2], xc[a][3]); *(u32x2*)(XC + o) = w; }
	v_pk_fma_f32 v[136:137], v[34:35], v[16:17], v[46:47] op_sel:[1,0,0]
	v_and_b32_sdwa v47, v138, v224 dst_sel:DWORD dst_unused:UNUSED_PAD src0_sel:WORD_1 src1_sel:DWORD
	v_add3_u32 v50, v138, v47, s81
	v_and_b32_sdwa v47, v137, v224 dst_sel:DWORD dst_unused:UNUSED_PAD src0_sel:WORD_1 src1_sel:DWORD
	v_and_b32_sdwa v51, v136, v224 dst_sel:DWORD dst_unused:UNUSED_PAD src0_sel:WORD_1 src1_sel:DWORD
	v_and_b32_sdwa v46, v139, v224 dst_sel:DWORD dst_unused:UNUSED_PAD src0_sel:WORD_1 src1_sel:DWORD
	v_add3_u32 v47, v137, v47, s81
	v_add3_u32 v51, v136, v51, s81
	v_add3_u32 v46, v139, v46, s81
	v_and_b32_e32 v47, 0xffff0000, v47
	v_and_b32_e32 v51, 0xffff0000, v51
	v_or_b32_sdwa v47, v47, v46 dst_sel:DWORD dst_unused:UNUSED_PAD src0_sel:DWORD src1_sel:WORD_1
	v_or_b32_sdwa v46, v51, v50 dst_sel:DWORD dst_unused:UNUSED_PAD src0_sel:DWORD src1_sel:WORD_1
	v_add_co_u32_e32 v50, vcc, s56, v166
	s_nop 1
	v_addc_co_u32_e32 v51, vcc, 0, v167, vcc
	flat_store_dwordx2 v[50:51], v[46:47]
	v_and_b32_sdwa v47, v42, v224 dst_sel:DWORD dst_unused:UNUSED_PAD src0_sel:WORD_1 src1_sel:DWORD
	v_and_b32_sdwa v46, v43, v224 dst_sel:DWORD dst_unused:UNUSED_PAD src0_sel:WORD_1 src1_sel:DWORD
	v_add3_u32 v42, v42, v47, s81
	v_and_b32_sdwa v47, v34, v224 dst_sel:DWORD dst_unused:UNUSED_PAD src0_sel:WORD_1 src1_sel:DWORD
	v_add3_u32 v43, v43, v46, s81
	v_and_b32_sdwa v46, v35, v224 dst_sel:DWORD dst_unused:UNUSED_PAD src0_sel:WORD_1 src1_sel:DWORD
	v_add3_u32 v34, v34, v47, s81
	v_add3_u32 v35, v35, v46, s81
	v_and_b32_e32 v34, 0xffff0000, v34
	v_and_b32_e32 v35, 0xffff0000, v35
	v_or_b32_sdwa v34, v34, v42 dst_sel:DWORD dst_unused:UNUSED_PAD src0_sel:DWORD src1_sel:WORD_1
	v_add_co_u32_e32 v42, vcc, s74, v166
	v_or_b32_sdwa v35, v35, v43 dst_sel:DWORD dst_unused:UNUSED_PAD src0_sel:DWORD src1_sel:WORD_1
	s_nop 0
	v_addc_co_u32_e32 v43, vcc, 0, v167, vcc
	v_mov_b32_e32 v46, v143
	flat_store_dwordx2 v[42:43], v[34:35]
	v_mov_b32_e32 v42, v133
	v_pk_mul_f32 v[50:51], v[46:47], v[6:7] op_sel_hi:[0,1]
	v_pk_mul_f32 v[46:47], v[46:47], v[52:53] op_sel_hi:[0,1]
	v_pk_fma_f32 v[50:51], v[42:43], v[2:3], v[50:51] op_sel_hi:[0,1,1]
	v_pk_fma_f32 v[42:43], v[42:43], v[40:41], v[46:47] op_sel_hi:[0,1,1]
	v_pk_fma_f32 v[42:43], v[62:63], v[44:45], v[42:43] op_sel_hi:[0,1,1]
	v_pk_fma_f32 v[134:135], v[64:65], v[48:49], v[42:43] op_sel_hi:[0,1,1]
	v_and_b32_sdwa v46, v134, v224 dst_sel:DWORD dst_unused:UNUSED_PAD src0_sel:WORD_1 src1_sel:DWORD
	v_pk_fma_f32 v[50:51], v[62:63], v[10:11], v[50:51] op_sel_hi:[0,1,1]
	v_add3_u32 v46, v134, v46, s81
	v_pk_fma_f32 v[132:133], v[64:65], v[14:15], v[50:51] op_sel_hi:[0,1,1]
	v_and_b32_e32 v64, 0xffff0000, v46
	v_mov_b32_e32 v46, v206
	v_mov_b32_e32 v47, v208
	v_and_b32_sdwa v43, v132, v224 dst_sel:DWORD dst_unused:UNUSED_PAD src0_sel:WORD_1 src1_sel:DWORD
	v_pk_add_f32 v[46:47], v[38:39], v[46:47]
	v_mov_b32_e32 v208, v207
	v_add3_u32 v62, v132, v43, s81
	v_and_b32_sdwa v43, v135, v224 dst_sel:DWORD dst_unused:UNUSED_PAD src0_sel:WORD_1 src1_sel:DWORD
	v_pk_add_f32 v[46:47], v[46:47], v[208:209]
	v_mov_b32_e32 v50, v170
	v_mov_b32_e32 v51, v172
	v_and_b32_sdwa v42, v133, v224 dst_sel:DWORD dst_unused:UNUSED_PAD src0_sel:WORD_1 src1_sel:DWORD
	v_add3_u32 v43, v135, v43, s81
	v_pk_add_f32 v[46:47], v[46:47], v[50:51]
	v_mov_b32_e32 v172, v171
	v_mov_b32_e32 v50, v148
	v_mov_b32_e32 v51, v212
	v_add3_u32 v42, v133, v42, s81
	v_and_b32_e32 v43, 0xffff0000, v43
	v_pk_add_f32 v[46:47], v[46:47], v[172:173]
	v_pk_add_f32 v[50:51], v[36:37], v[50:51]
	v_mov_b32_e32 v212, v149
	v_or_b32_sdwa v43, v43, v42 dst_sel:DWORD dst_unused:UNUSED_PAD src0_sel:DWORD src1_sel:WORD_1
	v_mul_f32_e32 v42, 0xbfb8aa3b, v46
	v_pk_add_f32 v[50:51], v[50:51], v[212:213]
	v_exp_f32_e32 v66, v42
	v_pk_add_f32 v[50:51], v[50:51], v[140:141]
	v_lshl_add_u64 v[34:35], s[30:31], 0, v[0:1]
	v_pk_add_f32 v[50:51], v[50:51], v[210:211]
	v_add_co_u32_e32 v144, vcc, s58, v34
	v_mul_f32_e32 v42, 0xbfb8aa3b, v50
	v_exp_f32_e32 v68, v42
	v_or_b32_sdwa v42, v64, v62 dst_sel:DWORD dst_unused:UNUSED_PAD src0_sel:DWORD src1_sel:WORD_1
	v_mul_f32_e32 v64, 0xbfb8aa3b, v47
	v_add_f32_e32 v62, 1.0, v66
	v_exp_f32_e32 v64, v64
	v_mul_f32_e32 v66, 0xbfb8aa3b, v51
	v_exp_f32_e32 v66, v66
	v_rcp_f32_e32 v140, v62
	v_add_f32_e32 v62, 1.0, v68
	v_rcp_f32_e32 v142, v62
	v_add_f32_e32 v62, 1.0, v64
	v_rcp_f32_e32 v141, v62
	v_add_f32_e32 v62, 1.0, v66
	v_rcp_f32_e32 v143, v62
	v_addc_co_u32_e32 v145, vcc, 0, v35, vcc
	flat_store_dwordx2 v[144:145], v[42:43]
	v_pk_mul_f32 v[42:43], v[46:47], v[140:141]
	v_pk_mul_f32 v[46:47], v[50:51], v[142:143]
	v_add_co_u32_e32 v144, vcc, s57, v34
	v_pk_mul_f32 v[50:51], v[56:57], v[46:47] op_sel_hi:[1,0]
	s_nop 0
	v_addc_co_u32_e32 v145, vcc, 0, v35, vcc
	v_pk_fma_f32 v[50:51], v[54:55], v[42:43], v[50:51] op_sel_hi:[1,0,1]
	s_nop 0
	v_pk_fma_f32 v[50:51], v[58:59], v[42:43], v[50:51] op_sel:[0,1,0]
	s_nop 0
	v_pk_fma_f32 v[140:141], v[60:61], v[46:47], v[50:51] op_sel:[0,1,0]
	v_pk_mul_f32 v[50:51], v[24:25], v[46:47] op_sel_hi:[1,0]
	s_nop 0
	v_pk_fma_f32 v[50:51], v[20:21], v[42:43], v[50:51] op_sel_hi:[1,0,1]
	s_nop 0
	v_pk_fma_f32 v[50:51], v[28:29], v[42:43], v[50:51] op_sel:[0,1,0]
	s_nop 0
	v_pk_fma_f32 v[142:143], v[32:33], v[46:47], v[50:51] op_sel:[0,1,0]
	v_and_b32_sdwa v51, v140, v224 dst_sel:DWORD dst_unused:UNUSED_PAD src0_sel:WORD_1 src1_sel:DWORD
	v_add3_u32 v62, v140, v51, s81
	v_and_b32_sdwa v51, v143, v224 dst_sel:DWORD dst_unused:UNUSED_PAD src0_sel:WORD_1 src1_sel:DWORD
	v_and_b32_sdwa v64, v142, v224 dst_sel:DWORD dst_unused:UNUSED_PAD src0_sel:WORD_1 src1_sel:DWORD
	v_and_b32_sdwa v50, v141, v224 dst_sel:DWORD dst_unused:UNUSED_PAD src0_sel:WORD_1 src1_sel:DWORD
; __device__ __forceinline__ unsigned pk2(float lo, float hi) { return f2bf(lo) | (f2bf(hi) << 16); }
; __device__ __forceinline__ void preproc_phase(Frame& F, int layer, int b, int cu_lo, int ncu) {
;     ...
;             const f32x4 cbv = *(const f32x4*)(cb + cc); f32x4 cwv[4];
; #pragma unroll
;             for (int j = 0; j < 4; ++j) cwv[j] = *(const f32x4*)(cw + j * D + cc);
;             float xc[4][4], q[4][4], k[4][4], v[4][4];
; #pragma unroll
;             for (int a = 0; a < 4; ++a)
; #pragma unroll
;                 for (int c = 0; c < 4; ++c) { float s = cbv[c];
; #pragma unroll
;                     for (int j = 0; j < 4; ++j) s += cwv[j][c] * xm[a + j][c];
;                     xc[a][c] = siluf_(s); }
;             const int nb = cc >> 2;
;             {   f32x4 w[4];
; #pragma unroll
;                 for (int c = 0; c < 4; ++c) w[c] = *(const f32x4*)(wq + nb * 16 + c * 4);
; #pragma unroll
;                 for (int a = 0; a < 4; ++a)
; #pragma unroll
;                     for (int d = 0; d < 4; ++d) q[a][d] = xc[a][0] * w[0][d] + xc[a][1] * w[1][d] + xc[a][2] * w[2][d] + xc[a][3] * w[3][d];
; #pragma unroll
;                 for (int c = 0; c < 4; ++c) w[c] = *(const f32x4*)(wk + nb * 16 + c * 4);
; #pragma unroll
;                 for (int a = 0; a < 4; ++a)
; #pragma unroll
;                     for (int d = 0; d < 4; ++d) k[a][d] = xc[a][0] * w[0][d] + xc[a][1] * w[1][d] + xc[a][2] * w[2][d] + xc[a][3] * w[3][d];
; #pragma unroll
;                 for (int c = 0; c < 4; ++c) w[c] = *(const f32x4*)(wv + nb * 16 + c * 4);
; #pragma unroll
;                 for (int a = 0; a < 4; ++a)
; #pragma unroll
;                     for (int d = 0; d < 4; ++d) v[a][d] = xm[a + 3][0] * w[0][d] + xm[a + 3][1] * w[1][d] + xm[a + 3][2] * w[2][d] + xm[a + 3][3] * w[3][d];
;             }
; #pragma unroll
;             for (int a = 0; a < 4; ++a) { const size_t o = (size_t)(t0 + a) * D + cc; u32x2 w;
;                 w.x = pk2(q[a][0], q[a][1]); w.y = pk2(q[a][2], q[a][3]); *(u32x2*)(MQ + o) = w;
;                 w.x = pk2(k[a][0], k[a][1]); w.y = pk2(k[a][2], k[a][3]); *(u32x2*)(MK + o) = w;
;                 w.x = pk2(v[a][0], v[a][1]); w.y = pk2(v[a][2], v[a][3]); *(u32x2*)(MV + o) = w;
;                 w.x = pk2(xc[a][0], xc[a][1]); w.y = pk2(xc[a][2], xc[a][3]); *(u32x2*)(XC + o) = w; }
	v_add3_u32 v51, v143, v51, s81
	v_add3_u32 v64, v142, v64, s81
	v_add3_u32 v50, v141, v50, s81
	v_and_b32_e32 v51, 0xffff0000, v51
	v_and_b32_e32 v64, 0xffff0000, v64
	v_or_b32_sdwa v51, v51, v50 dst_sel:DWORD dst_unused:UNUSED_PAD src0_sel:DWORD src1_sel:WORD_1
	v_or_b32_sdwa v50, v64, v62 dst_sel:DWORD dst_unused:UNUSED_PAD src0_sel:DWORD src1_sel:WORD_1
	flat_store_dwordx2 v[144:145], v[50:51]
	v_pk_mul_f32 v[50:51], v[22:23], v[46:47] op_sel_hi:[1,0]
	v_add_co_u32_e32 v144, vcc, s56, v34
	v_pk_fma_f32 v[50:51], v[18:19], v[42:43], v[50:51] op_sel_hi:[1,0,1]
	s_nop 0
	v_addc_co_u32_e32 v145, vcc, 0, v35, vcc
	v_pk_fma_f32 v[50:51], v[26:27], v[42:43], v[50:51] op_sel:[0,1,0]
	v_add_co_u32_e32 v34, vcc, s74, v34
	v_pk_fma_f32 v[170:171], v[46:47], v[30:31], v[50:51] op_sel:[1,0,0]
	v_pk_mul_f32 v[50:51], v[8:9], v[46:47] op_sel_hi:[1,0]
	v_addc_co_u32_e32 v35, vcc, 0, v35, vcc
	v_pk_fma_f32 v[50:51], v[4:5], v[42:43], v[50:51] op_sel_hi:[1,0,1]
	s_nop 0
	v_pk_fma_f32 v[50:51], v[12:13], v[42:43], v[50:51] op_sel:[0,1,0]
	s_nop 0
	v_pk_fma_f32 v[172:173], v[46:47], v[16:17], v[50:51] op_sel:[1,0,0]
	v_and_b32_sdwa v51, v170, v224 dst_sel:DWORD dst_unused:UNUSED_PAD src0_sel:WORD_1 src1_sel:DWORD
	v_add3_u32 v62, v170, v51, s81
	v_and_b32_sdwa v51, v173, v224 dst_sel:DWORD dst_unused:UNUSED_PAD src0_sel:WORD_1 src1_sel:DWORD
	v_and_b32_sdwa v64, v172, v224 dst_sel:DWORD dst_unused:UNUSED_PAD src0_sel:WORD_1 src1_sel:DWORD
	v_and_b32_sdwa v50, v171, v224 dst_sel:DWORD dst_unused:UNUSED_PAD src0_sel:WORD_1 src1_sel:DWORD
	v_add3_u32 v51, v173, v51, s81
	v_add3_u32 v64, v172, v64, s81
	v_add3_u32 v50, v171, v50, s81
	v_and_b32_e32 v51, 0xffff0000, v51
	v_and_b32_e32 v64, 0xffff0000, v64
	v_or_b32_sdwa v51, v51, v50 dst_sel:DWORD dst_unused:UNUSED_PAD src0_sel:DWORD src1_sel:WORD_1
	v_or_b32_sdwa v50, v64, v62 dst_sel:DWORD dst_unused:UNUSED_PAD src0_sel:DWORD src1_sel:WORD_1
	flat_store_dwordx2 v[144:145], v[50:51]
	v_and_b32_sdwa v50, v43, v224 dst_sel:DWORD dst_unused:UNUSED_PAD src0_sel:WORD_1 src1_sel:DWORD
	v_and_b32_sdwa v51, v42, v224 dst_sel:DWORD dst_unused:UNUSED_PAD src0_sel:WORD_1 src1_sel:DWORD
	v_add3_u32 v42, v42, v51, s81
	v_add3_u32 v43, v43, v50, s81
	v_and_b32_sdwa v50, v47, v224 dst_sel:DWORD dst_unused:UNUSED_PAD src0_sel:WORD_1 src1_sel:DWORD
	v_and_b32_sdwa v51, v46, v224 dst_sel:DWORD dst_unused:UNUSED_PAD src0_sel:WORD_1 src1_sel:DWORD
	v_add3_u32 v47, v47, v50, s81
	v_add3_u32 v46, v46, v51, s81
	v_and_b32_e32 v47, 0xffff0000, v47
	v_and_b32_e32 v46, 0xffff0000, v46
	v_or_b32_sdwa v43, v47, v43 dst_sel:DWORD dst_unused:UNUSED_PAD src0_sel:DWORD src1_sel:WORD_1
	v_or_b32_sdwa v42, v46, v42 dst_sel:DWORD dst_unused:UNUSED_PAD src0_sel:DWORD src1_sel:WORD_1
	v_mov_b32_e32 v46, v81
	flat_store_dwordx2 v[34:35], v[42:43]
	v_mov_b32_e32 v42, v79
	v_pk_mul_f32 v[50:51], v[46:47], v[6:7] op_sel_hi:[0,1]
	v_pk_mul_f32 v[46:47], v[46:47], v[52:53] op_sel_hi:[0,1]
	v_pk_fma_f32 v[50:51], v[42:43], v[2:3], v[50:51] op_sel_hi:[0,1,1]
	v_mov_b32_e32 v62, v77
	v_pk_fma_f32 v[42:43], v[42:43], v[40:41], v[46:47] op_sel_hi:[0,1,1]
	v_mov_b32_e32 v64, v75
	v_pk_fma_f32 v[42:43], v[62:63], v[44:45], v[42:43] op_sel_hi:[0,1,1]
	v_pk_fma_f32 v[148:149], v[64:65], v[48:49], v[42:43] op_sel_hi:[0,1,1]
	v_and_b32_sdwa v46, v148, v224 dst_sel:DWORD dst_unused:UNUSED_PAD src0_sel:WORD_1 src1_sel:DWORD
	v_pk_fma_f32 v[50:51], v[62:63], v[10:11], v[50:51] op_sel_hi:[0,1,1]
	v_add3_u32 v46, v148, v46, s81
	v_pk_fma_f32 v[144:145], v[64:65], v[14:15], v[50:51] op_sel_hi:[0,1,1]
	v_and_b32_e32 v64, 0xffff0000, v46
	v_mov_b32_e32 v46, v202
	v_mov_b32_e32 v47, v204
	v_and_b32_sdwa v43, v144, v224 dst_sel:DWORD dst_unused:UNUSED_PAD src0_sel:WORD_1 src1_sel:DWORD
	v_pk_add_f32 v[46:47], v[38:39], v[46:47]
	v_mov_b32_e32 v204, v203
	v_add3_u32 v62, v144, v43, s81
	v_and_b32_sdwa v43, v149, v224 dst_sel:DWORD dst_unused:UNUSED_PAD src0_sel:WORD_1 src1_sel:DWORD
	v_pk_add_f32 v[46:47], v[46:47], v[204:205]
	v_mov_b32_e32 v50, v190
	v_mov_b32_e32 v51, v192
	v_and_b32_sdwa v42, v145, v224 dst_sel:DWORD dst_unused:UNUSED_PAD src0_sel:WORD_1 src1_sel:DWORD
	v_add3_u32 v43, v149, v43, s81
	v_pk_add_f32 v[46:47], v[46:47], v[50:51]
	v_mov_b32_e32 v192, v191
	v_mov_b32_e32 v50, v180
	v_mov_b32_e32 v51, v182
	v_add3_u32 v42, v145, v42, s81
	v_and_b32_e32 v43, 0xffff0000, v43
	v_pk_add_f32 v[46:47], v[46:47], v[192:193]
	v_pk_add_f32 v[50:51], v[36:37], v[50:51]
	v_mov_b32_e32 v182, v181
	v_or_b32_sdwa v43, v43, v42 dst_sel:DWORD dst_unused:UNUSED_PAD src0_sel:DWORD src1_sel:WORD_1
	v_mul_f32_e32 v42, 0xbfb8aa3b, v46
	v_pk_add_f32 v[50:51], v[50:51], v[182:183]
	v_mov_b32_e32 v75, v176
	v_exp_f32_e32 v66, v42
	v_pk_add_f32 v[50:51], v[50:51], v[74:75]
	v_mov_b32_e32 v176, v175
	v_pk_add_f32 v[50:51], v[50:51], v[176:177]
	v_lshl_add_u64 v[34:35], s[34:35], 0, v[0:1]
	v_mul_f32_e32 v42, 0xbfb8aa3b, v50
	v_exp_f32_e32 v68, v42
	v_or_b32_sdwa v42, v64, v62 dst_sel:DWORD dst_unused:UNUSED_PAD src0_sel:DWORD src1_sel:WORD_1
	v_mul_f32_e32 v64, 0xbfb8aa3b, v47
	v_add_f32_e32 v62, 1.0, v66
	v_exp_f32_e32 v64, v64
	v_mul_f32_e32 v66, 0xbfb8aa3b, v51
	v_exp_f32_e32 v66, v66
	v_rcp_f32_e32 v74, v62
	v_add_f32_e32 v62, 1.0, v68
	v_rcp_f32_e32 v76, v62
	v_add_f32_e32 v62, 1.0, v64
	v_rcp_f32_e32 v75, v62
	v_add_f32_e32 v62, 1.0, v66
	v_rcp_f32_e32 v77, v62
	v_add_co_u32_e32 v78, vcc, s58, v34
	s_nop 1
	v_addc_co_u32_e32 v79, vcc, 0, v35, vcc
	flat_store_dwordx2 v[78:79], v[42:43]
	v_pk_mul_f32 v[42:43], v[46:47], v[74:75]
	v_pk_mul_f32 v[46:47], v[50:51], v[76:77]
	v_add_co_u32_e32 v74, vcc, s57, v34
	v_pk_mul_f32 v[50:51], v[56:57], v[46:47] op_sel_hi:[1,0]
	s_nop 0
; __device__ __forceinline__ unsigned pk2(float lo, float hi) { return f2bf(lo) | (f2bf(hi) << 16); }
; __device__ __forceinline__ float siluf_(float x) { return x * __builtin_amdgcn_rcpf(1.f + __expf(-x)); }
; __device__ __forceinline__ void preproc_phase(Frame& F, int layer, int b, int cu_lo, int ncu) {
;     ...
;                 for (int c = 0; c < 4; ++c) { float s = cbv[c];
; #pragma unroll
;                     for (int j = 0; j < 4; ++j) s += cwv[j][c] * xm[a + j][c];
;                     xc[a][c] = siluf_(s); }
;             const int nb = cc >> 2;
;             {   f32x4 w[4];
; #pragma unroll
;                 for (int c = 0; c < 4; ++c) w[c] = *(const f32x4*)(wq + nb * 16 + c * 4);
; #pragma unroll
;                 for (int a = 0; a < 4; ++a)
; #pragma unroll
;                     for (int d = 0; d < 4; ++d) q[a][d] = xc[a][0] * w[0][d] + xc[a][1] * w[1][d] + xc[a][2] * w[2][d] + xc[a][3] * w[3][d];
; #pragma unroll
;                 for (int c = 0; c < 4; ++c) w[c] = *(const f32x4*)(wk + nb * 16 + c * 4);
; #pragma unroll
;                 for (int a = 0; a < 4; ++a)
; #pragma unroll
;                     for (int d = 0; d < 4; ++d) k[a][d] = xc[a][0] * w[0][d] + xc[a][1] * w[1][d] + xc[a][2] * w[2][d] + xc[a][3] * w[3][d];
; #pragma unroll
;                 for (int c = 0; c < 4; ++c) w[c] = *(const f32x4*)(wv + nb * 16 + c * 4);
; #pragma unroll
;                 for (int a = 0; a < 4; ++a)
; #pragma unroll
;                     for (int d = 0; d < 4; ++d) v[a][d] = xm[a + 3][0] * w[0][d] + xm[a + 3][1] * w[1][d] + xm[a + 3][2] * w[2][d] + xm[a + 3][3] * w[3][d];
;             }
; #pragma unroll
;             for (int a = 0; a < 4; ++a) { const size_t o = (size_t)(t0 + a) * D + cc; u32x2 w;
;                 w.x = pk2(q[a][0], q[a][1]); w.y = pk2(q[a][2], q[a][3]); *(u32x2*)(MQ + o) = w;
;                 w.x = pk2(k[a][0], k[a][1]); w.y = pk2(k[a][2], k[a][3]); *(u32x2*)(MK + o) = w;
;                 w.x = pk2(v[a][0], v[a][1]); w.y = pk2(v[a][2], v[a][3]); *(u32x2*)(MV + o) = w;
;                 w.x = pk2(xc[a][0], xc[a][1]); w.y = pk2(xc[a][2], xc[a][3]); *(u32x2*)(XC + o) = w; }
	v_addc_co_u32_e32 v75, vcc, 0, v35, vcc
	v_pk_fma_f32 v[50:51], v[54:55], v[42:43], v[50:51] op_sel_hi:[1,0,1]
	s_nop 0
	v_pk_fma_f32 v[50:51], v[58:59], v[42:43], v[50:51] op_sel:[0,1,0]
	s_nop 0
	v_pk_fma_f32 v[174:175], v[60:61], v[46:47], v[50:51] op_sel:[0,1,0]
	v_pk_mul_f32 v[50:51], v[24:25], v[46:47] op_sel_hi:[1,0]
	s_nop 0
	v_pk_fma_f32 v[50:51], v[20:21], v[42:43], v[50:51] op_sel_hi:[1,0,1]
	s_nop 0
	v_pk_fma_f32 v[50:51], v[28:29], v[42:43], v[50:51] op_sel:[0,1,0]
	s_nop 0
	v_pk_fma_f32 v[176:177], v[32:33], v[46:47], v[50:51] op_sel:[0,1,0]
	v_and_b32_sdwa v51, v174, v224 dst_sel:DWORD dst_unused:UNUSED_PAD src0_sel:WORD_1 src1_sel:DWORD
	v_add3_u32 v62, v174, v51, s81
	v_and_b32_sdwa v51, v177, v224 dst_sel:DWORD dst_unused:UNUSED_PAD src0_sel:WORD_1 src1_sel:DWORD
	v_and_b32_sdwa v64, v176, v224 dst_sel:DWORD dst_unused:UNUSED_PAD src0_sel:WORD_1 src1_sel:DWORD
	v_and_b32_sdwa v50, v175, v224 dst_sel:DWORD dst_unused:UNUSED_PAD src0_sel:WORD_1 src1_sel:DWORD
	v_add3_u32 v51, v177, v51, s81
	v_add3_u32 v64, v176, v64, s81
	v_add3_u32 v50, v175, v50, s81
	v_and_b32_e32 v51, 0xffff0000, v51
	v_and_b32_e32 v64, 0xffff0000, v64
	v_or_b32_sdwa v51, v51, v50 dst_sel:DWORD dst_unused:UNUSED_PAD src0_sel:DWORD src1_sel:WORD_1
	v_or_b32_sdwa v50, v64, v62 dst_sel:DWORD dst_unused:UNUSED_PAD src0_sel:DWORD src1_sel:WORD_1
	flat_store_dwordx2 v[74:75], v[50:51]
	v_pk_mul_f32 v[50:51], v[22:23], v[46:47] op_sel_hi:[1,0]
	v_add_co_u32_e32 v74, vcc, s56, v34
	v_pk_fma_f32 v[50:51], v[18:19], v[42:43], v[50:51] op_sel_hi:[1,0,1]
	s_nop 0
	v_addc_co_u32_e32 v75, vcc, 0, v35, vcc
	v_pk_fma_f32 v[50:51], v[26:27], v[42:43], v[50:51] op_sel:[0,1,0]
	v_add_co_u32_e32 v34, vcc, s74, v34
	v_pk_fma_f32 v[190:191], v[46:47], v[30:31], v[50:51] op_sel:[1,0,0]
	v_pk_mul_f32 v[50:51], v[8:9], v[46:47] op_sel_hi:[1,0]
	v_addc_co_u32_e32 v35, vcc, 0, v35, vcc
	v_pk_fma_f32 v[50:51], v[4:5], v[42:43], v[50:51] op_sel_hi:[1,0,1]
	s_nop 0
	v_pk_fma_f32 v[50:51], v[12:13], v[42:43], v[50:51] op_sel:[0,1,0]
	s_nop 0
	v_pk_fma_f32 v[192:193], v[46:47], v[16:17], v[50:51] op_sel:[1,0,0]
	v_and_b32_sdwa v51, v190, v224 dst_sel:DWORD dst_unused:UNUSED_PAD src0_sel:WORD_1 src1_sel:DWORD
	v_add3_u32 v62, v190, v51, s81
	v_and_b32_sdwa v51, v193, v224 dst_sel:DWORD dst_unused:UNUSED_PAD src0_sel:WORD_1 src1_sel:DWORD
	v_and_b32_sdwa v64, v192, v224 dst_sel:DWORD dst_unused:UNUSED_PAD src0_sel:WORD_1 src1_sel:DWORD
	v_and_b32_sdwa v50, v191, v224 dst_sel:DWORD dst_unused:UNUSED_PAD src0_sel:WORD_1 src1_sel:DWORD
	v_add3_u32 v51, v193, v51, s81
	v_add3_u32 v64, v192, v64, s81
	v_add3_u32 v50, v191, v50, s81
	v_and_b32_e32 v51, 0xffff0000, v51
	v_and_b32_e32 v64, 0xffff0000, v64
	v_or_b32_sdwa v51, v51, v50 dst_sel:DWORD dst_unused:UNUSED_PAD src0_sel:DWORD src1_sel:WORD_1
	v_or_b32_sdwa v50, v64, v62 dst_sel:DWORD dst_unused:UNUSED_PAD src0_sel:DWORD src1_sel:WORD_1
	flat_store_dwordx2 v[74:75], v[50:51]
	v_and_b32_sdwa v50, v43, v224 dst_sel:DWORD dst_unused:UNUSED_PAD src0_sel:WORD_1 src1_sel:DWORD
	v_and_b32_sdwa v51, v42, v224 dst_sel:DWORD dst_unused:UNUSED_PAD src0_sel:WORD_1 src1_sel:DWORD
	v_add3_u32 v42, v42, v51, s81
	v_add3_u32 v43, v43, v50, s81
	v_and_b32_sdwa v50, v47, v224 dst_sel:DWORD dst_unused:UNUSED_PAD src0_sel:WORD_1 src1_sel:DWORD
	v_and_b32_sdwa v51, v46, v224 dst_sel:DWORD dst_unused:UNUSED_PAD src0_sel:WORD_1 src1_sel:DWORD
	v_add3_u32 v47, v47, v50, s81
	v_add3_u32 v46, v46, v51, s81
	v_and_b32_e32 v47, 0xffff0000, v47
	v_and_b32_e32 v46, 0xffff0000, v46
	v_or_b32_sdwa v43, v47, v43 dst_sel:DWORD dst_unused:UNUSED_PAD src0_sel:DWORD src1_sel:WORD_1
	v_or_b32_sdwa v42, v46, v42 dst_sel:DWORD dst_unused:UNUSED_PAD src0_sel:DWORD src1_sel:WORD_1
	v_mov_b32_e32 v46, v69
	flat_store_dwordx2 v[34:35], v[42:43]
	v_mov_b32_e32 v42, v63
	v_pk_mul_f32 v[6:7], v[46:47], v[6:7] op_sel_hi:[0,1]
	v_pk_fma_f32 v[2:3], v[42:43], v[2:3], v[6:7] op_sel_hi:[0,1,1]
	v_mov_b32_e32 v6, v67
	v_pk_fma_f32 v[2:3], v[6:7], v[10:11], v[2:3] op_sel_hi:[0,1,1]
	v_mov_b32_e32 v10, v65
	v_pk_fma_f32 v[180:181], v[10:11], v[14:15], v[2:3] op_sel_hi:[0,1,1]
	v_pk_mul_f32 v[2:3], v[46:47], v[52:53] op_sel_hi:[0,1]
	v_pk_fma_f32 v[2:3], v[42:43], v[40:41], v[2:3] op_sel_hi:[0,1,1]
	v_pk_fma_f32 v[2:3], v[6:7], v[44:45], v[2:3] op_sel_hi:[0,1,1]
	v_pk_fma_f32 v[182:183], v[10:11], v[48:49], v[2:3] op_sel_hi:[0,1,1]
	v_and_b32_sdwa v6, v182, v224 dst_sel:DWORD dst_unused:UNUSED_PAD src0_sel:WORD_1 src1_sel:DWORD
	v_add3_u32 v6, v182, v6, s81
	v_and_b32_e32 v41, 0xffff0000, v6
	v_mov_b32_e32 v6, v198
	v_mov_b32_e32 v7, v200
	v_and_b32_sdwa v3, v180, v224 dst_sel:DWORD dst_unused:UNUSED_PAD src0_sel:WORD_1 src1_sel:DWORD
	v_pk_add_f32 v[6:7], v[38:39], v[6:7]
	v_mov_b32_e32 v200, v199
	v_add3_u32 v40, v180, v3, s81
	v_and_b32_sdwa v3, v183, v224 dst_sel:DWORD dst_unused:UNUSED_PAD src0_sel:WORD_1 src1_sel:DWORD
	v_pk_add_f32 v[6:7], v[6:7], v[200:201]
	v_mov_b32_e32 v10, v194
	v_mov_b32_e32 v11, v196
	v_and_b32_sdwa v2, v181, v224 dst_sel:DWORD dst_unused:UNUSED_PAD src0_sel:WORD_1 src1_sel:DWORD
	v_add3_u32 v3, v183, v3, s81
	v_pk_add_f32 v[6:7], v[6:7], v[10:11]
	v_mov_b32_e32 v196, v195
	v_mov_b32_e32 v10, v186
	v_mov_b32_e32 v11, v188
	v_add3_u32 v2, v181, v2, s81
	v_and_b32_e32 v3, 0xffff0000, v3
	v_pk_add_f32 v[6:7], v[6:7], v[196:197]
	v_pk_add_f32 v[10:11], v[36:37], v[10:11]
	v_mov_b32_e32 v188, v187
	v_or_b32_sdwa v3, v3, v2 dst_sel:DWORD dst_unused:UNUSED_PAD src0_sel:DWORD src1_sel:WORD_1
	v_mul_f32_e32 v2, 0xbfb8aa3b, v6
	v_pk_add_f32 v[10:11], v[10:11], v[188:189]
	v_mov_b32_e32 v14, v178
	v_mov_b32_e32 v15, v184
	v_exp_f32_e32 v38, v2
	v_pk_add_f32 v[10:11], v[10:11], v[14:15]
; __device__ __forceinline__ unsigned pk2(float lo, float hi) { return f2bf(lo) | (f2bf(hi) << 16); }
; __device__ __forceinline__ void preproc_phase(Frame& F, int layer, int b, int cu_lo, int ncu) {
;     ...
;             for (int a = 0; a < 4; ++a) { const size_t o = (size_t)(t0 + a) * D + cc; u32x2 w;
;                 w.x = pk2(q[a][0], q[a][1]); w.y = pk2(q[a][2], q[a][3]); *(u32x2*)(MQ + o) = w;
;                 w.x = pk2(k[a][0], k[a][1]); w.y = pk2(k[a][2], k[a][3]); *(u32x2*)(MK + o) = w;
;                 w.x = pk2(v[a][0], v[a][1]); w.y = pk2(v[a][2], v[a][3]); *(u32x2*)(MV + o) = w;
;                 w.x = pk2(xc[a][0], xc[a][1]); w.y = pk2(xc[a][2], xc[a][3]); *(u32x2*)(XC + o) = w; }
; #pragma unroll
;             for (int c = 0; c < 4; ++c) {
;                 f32x4 wiv = *(const f32x4*)(wi + (size_t)(cc + c) * 4), wfv = *(const f32x4*)(wf + (size_t)(cc + c) * 4);
; #pragma unroll
;                 for (int a = 0; a < 4; ++a)
; #pragma unroll
;                     for (int hh = 0; hh < 4; ++hh) { ai[a][hh] += q[a][c] * wiv[hh]; af[a][hh] += q[a][c] * wfv[hh]; }
;                 wiv = *(const f32x4*)(wi + (size_t)(1024 + cc + c) * 4); wfv = *(const f32x4*)(wf + (size_t)(1024 + cc + c) * 4);
; #pragma unroll
;                 for (int a = 0; a < 4; ++a)
; #pragma unroll
;                     for (int hh = 0; hh < 4; ++hh) { ai[a][hh] += k[a][c] * wiv[hh]; af[a][hh] += k[a][c] * wfv[hh]; }
;                 wiv = *(const f32x4*)(wi + (size_t)(2048 + cc + c) * 4); wfv = *(const f32x4*)(wf + (size_t)(2048 + cc + c) * 4);
; #pragma unroll
;                 for (int a = 0; a < 4; ++a)
; #pragma unroll
;                     for (int hh = 0; hh < 4; ++hh) { ai[a][hh] += v[a][c] * wiv[hh]; af[a][hh] += v[a][c] * wfv[hh]; }
;             }
	v_mov_b32_e32 v184, v179
	v_pk_add_f32 v[10:11], v[10:11], v[184:185]
	v_mul_f32_e32 v36, 0xbfb8aa3b, v7
	v_mul_f32_e32 v2, 0xbfb8aa3b, v10
	v_exp_f32_e32 v15, v2
	v_exp_f32_e32 v37, v36
	v_mul_f32_e32 v36, 0xbfb8aa3b, v11
	v_add_f32_e32 v14, 1.0, v38
	v_exp_f32_e32 v38, v36
	v_add_f32_e32 v15, 1.0, v15
	v_rcp_f32_e32 v36, v15
	v_add_f32_e32 v15, 1.0, v37
	v_add_f32_e32 v37, 1.0, v38
	v_rcp_f32_e32 v14, v14
	v_rcp_f32_e32 v15, v15
	v_rcp_f32_e32 v37, v37
	v_lshl_add_u64 v[34:35], s[36:37], 0, v[0:1]
	v_add_co_u32_e32 v38, vcc, s58, v34
	v_or_b32_sdwa v2, v41, v40 dst_sel:DWORD dst_unused:UNUSED_PAD src0_sel:DWORD src1_sel:WORD_1
	s_nop 0
	v_addc_co_u32_e32 v39, vcc, 0, v35, vcc
	flat_store_dwordx2 v[38:39], v[2:3]
	v_pk_mul_f32 v[2:3], v[6:7], v[14:15]
	v_pk_mul_f32 v[6:7], v[10:11], v[36:37]
	s_nop 0
	v_pk_mul_f32 v[10:11], v[56:57], v[6:7] op_sel_hi:[1,0]
	v_pk_mul_f32 v[8:9], v[8:9], v[6:7] op_sel_hi:[1,0]
	v_pk_fma_f32 v[10:11], v[54:55], v[2:3], v[10:11] op_sel_hi:[1,0,1]
	v_pk_fma_f32 v[4:5], v[4:5], v[2:3], v[8:9] op_sel_hi:[1,0,1]
	v_pk_fma_f32 v[10:11], v[58:59], v[2:3], v[10:11] op_sel:[0,1,0]
	v_pk_fma_f32 v[4:5], v[12:13], v[2:3], v[4:5] op_sel:[0,1,0]
	v_pk_fma_f32 v[178:179], v[60:61], v[6:7], v[10:11] op_sel:[0,1,0]
	v_pk_mul_f32 v[10:11], v[24:25], v[6:7] op_sel_hi:[1,0]
	v_pk_fma_f32 v[188:189], v[6:7], v[16:17], v[4:5] op_sel:[1,0,0]
	v_pk_fma_f32 v[10:11], v[20:21], v[2:3], v[10:11] op_sel_hi:[1,0,1]
	v_and_b32_sdwa v9, v188, v224 dst_sel:DWORD dst_unused:UNUSED_PAD src0_sel:WORD_1 src1_sel:DWORD
	v_pk_fma_f32 v[10:11], v[28:29], v[2:3], v[10:11] op_sel:[0,1,0]
	v_add3_u32 v9, v188, v9, s81
	v_pk_fma_f32 v[184:185], v[32:33], v[6:7], v[10:11] op_sel:[0,1,0]
	v_and_b32_sdwa v11, v178, v224 dst_sel:DWORD dst_unused:UNUSED_PAD src0_sel:WORD_1 src1_sel:DWORD
	v_add3_u32 v14, v178, v11, s81
	v_and_b32_sdwa v11, v185, v224 dst_sel:DWORD dst_unused:UNUSED_PAD src0_sel:WORD_1 src1_sel:DWORD
	v_and_b32_sdwa v15, v184, v224 dst_sel:DWORD dst_unused:UNUSED_PAD src0_sel:WORD_1 src1_sel:DWORD
	v_and_b32_sdwa v10, v179, v224 dst_sel:DWORD dst_unused:UNUSED_PAD src0_sel:WORD_1 src1_sel:DWORD
	v_add3_u32 v11, v185, v11, s81
	v_add3_u32 v15, v184, v15, s81
	v_add3_u32 v10, v179, v10, s81
	v_and_b32_e32 v11, 0xffff0000, v11
	v_and_b32_e32 v15, 0xffff0000, v15
	v_or_b32_sdwa v11, v11, v10 dst_sel:DWORD dst_unused:UNUSED_PAD src0_sel:DWORD src1_sel:WORD_1
	v_or_b32_sdwa v10, v15, v14 dst_sel:DWORD dst_unused:UNUSED_PAD src0_sel:DWORD src1_sel:WORD_1
	v_add_co_u32_e32 v14, vcc, s57, v34
	v_and_b32_e32 v9, 0xffff0000, v9
	s_nop 0
	v_addc_co_u32_e32 v15, vcc, 0, v35, vcc
	flat_store_dwordx2 v[14:15], v[10:11]
	v_pk_mul_f32 v[10:11], v[22:23], v[6:7] op_sel_hi:[1,0]
	s_nop 0
	v_pk_fma_f32 v[10:11], v[18:19], v[2:3], v[10:11] op_sel_hi:[1,0,1]
	s_nop 0
	v_pk_fma_f32 v[10:11], v[26:27], v[2:3], v[10:11] op_sel:[0,1,0]
	s_nop 0
	v_pk_fma_f32 v[186:187], v[6:7], v[30:31], v[10:11] op_sel:[1,0,0]
	s_nop 0
	v_and_b32_sdwa v5, v186, v224 dst_sel:DWORD dst_unused:UNUSED_PAD src0_sel:WORD_1 src1_sel:DWORD
	v_add3_u32 v8, v186, v5, s81
	v_and_b32_sdwa v5, v189, v224 dst_sel:DWORD dst_unused:UNUSED_PAD src0_sel:WORD_1 src1_sel:DWORD
	v_and_b32_sdwa v4, v187, v224 dst_sel:DWORD dst_unused:UNUSED_PAD src0_sel:WORD_1 src1_sel:DWORD
	v_add3_u32 v5, v189, v5, s81
	v_add3_u32 v4, v187, v4, s81
	v_and_b32_e32 v5, 0xffff0000, v5
	v_or_b32_sdwa v5, v5, v4 dst_sel:DWORD dst_unused:UNUSED_PAD src0_sel:DWORD src1_sel:WORD_1
	v_or_b32_sdwa v4, v9, v8 dst_sel:DWORD dst_unused:UNUSED_PAD src0_sel:DWORD src1_sel:WORD_1
	v_add_co_u32_e32 v8, vcc, s56, v34
	s_nop 1
	v_addc_co_u32_e32 v9, vcc, 0, v35, vcc
	flat_store_dwordx2 v[8:9], v[4:5]
	v_and_b32_sdwa v4, v3, v224 dst_sel:DWORD dst_unused:UNUSED_PAD src0_sel:WORD_1 src1_sel:DWORD
	v_and_b32_sdwa v5, v2, v224 dst_sel:DWORD dst_unused:UNUSED_PAD src0_sel:WORD_1 src1_sel:DWORD
	v_add3_u32 v3, v3, v4, s81
	v_and_b32_sdwa v4, v7, v224 dst_sel:DWORD dst_unused:UNUSED_PAD src0_sel:WORD_1 src1_sel:DWORD
	v_add3_u32 v2, v2, v5, s81
	v_and_b32_sdwa v5, v6, v224 dst_sel:DWORD dst_unused:UNUSED_PAD src0_sel:WORD_1 src1_sel:DWORD
	v_add3_u32 v4, v7, v4, s81
	v_add3_u32 v5, v6, v5, s81
	v_and_b32_e32 v4, 0xffff0000, v4
	v_and_b32_e32 v5, 0xffff0000, v5
	v_or_b32_sdwa v3, v4, v3 dst_sel:DWORD dst_unused:UNUSED_PAD src0_sel:DWORD src1_sel:WORD_1
	v_add_co_u32_e32 v4, vcc, s74, v34
	v_or_b32_sdwa v2, v5, v2 dst_sel:DWORD dst_unused:UNUSED_PAD src0_sel:DWORD src1_sel:WORD_1
	s_nop 0
	v_addc_co_u32_e32 v5, vcc, 0, v35, vcc
	flat_store_dwordx2 v[4:5], v[2:3]
	v_lshl_add_u64 v[2:3], v[72:73], 0, v[88:89]
	v_lshl_add_u64 v[26:27], v[2:3], 0, s[96:97]
	v_add_co_u32_e32 v30, vcc, s70, v26
	v_lshl_add_u64 v[2:3], v[70:71], 0, v[88:89]
	s_nop 0
	v_addc_co_u32_e32 v31, vcc, 0, v27, vcc
	flat_load_dwordx4 v[194:197], v[26:27]
	flat_load_dwordx4 v[202:205], v[30:31]
	v_lshl_add_u64 v[54:55], v[2:3], 0, s[96:97]
	v_add_co_u32_e32 v58, vcc, s70, v54
	flat_load_dwordx4 v[198:201], v[54:55]
	s_nop 0
	v_addc_co_u32_e32 v59, vcc, 0, v55, vcc
	flat_load_dwordx4 v[206:209], v[58:59]
	flat_load_dwordx4 v[6:9], v[26:27] offset:16
	v_add_co_u32_e32 v32, vcc, s86, v26
	flat_load_dwordx4 v[2:5], v[54:55] offset:16
	s_nop 0
	v_addc_co_u32_e32 v33, vcc, 0, v27, vcc
	flat_load_dwordx4 v[10:13], v[30:31] offset:16
	flat_load_dwordx4 v[18:21], v[32:33]
	flat_load_dwordx4 v[14:17], v[32:33] offset:16
	flat_load_dwordx4 v[22:25], v[26:27] offset:32
	s_nop 0
	flat_load_dwordx4 v[26:29], v[26:27] offset:48
	s_nop 0
	flat_load_dwordx4 v[70:73], v[30:31] offset:32
	flat_load_dwordx4 v[66:69], v[30:31] offset:48
	flat_load_dwordx4 v[78:81], v[32:33] offset:32
	flat_load_dwordx4 v[74:77], v[32:33] offset:48
	v_add_co_u32_e32 v62, vcc, s86, v54
	s_add_u32 s96, s96, 0x1000
	s_nop 0
	v_addc_co_u32_e32 v63, vcc, 0, v55, vcc
	flat_load_dwordx4 v[30:33], v[62:63]
	flat_load_dwordx4 v[34:37], v[58:59] offset:16
	flat_load_dwordx4 v[38:41], v[62:63] offset:16
	flat_load_dwordx4 v[42:45], v[54:55] offset:32
	flat_load_dwordx4 v[46:49], v[58:59] offset:32
	flat_load_dwordx4 v[50:53], v[62:63] offset:32
	s_nop 0
	flat_load_dwordx4 v[54:57], v[54:55] offset:48
	s_nop 0
	flat_load_dwordx4 v[58:61], v[58:59] offset:48
	s_nop 0
	flat_load_dwordx4 v[62:65], v[62:63] offset:48
	s_addc_u32 s97, s97, 0
	s_add_u32 s28, s28, 0x200
	s_addc_u32 s29, s29, 0
	s_add_u32 s30, s30, 0x200
	s_addc_u32 s31, s31, 0
	s_add_u32 s34, s34, 0x200
	s_addc_u32 s35, s35, 0
	s_add_u32 s36, s36, 0x200
	s_addc_u32 s37, s37, 0
	s_add_u32 s38, s38, 0x200
	s_addc_u32 s39, s39, 0
	s_add_u32 s40, s40, 0x200
	s_addc_u32 s41, s41, 0
	s_add_u32 s42, s42, 0x200
	s_addc_u32 s43, s43, 0
	s_add_u32 s52, s52, 0x200
	s_addc_u32 s53, s53, 0
	s_add_u32 s60, s60, 0x200
	s_addc_u32 s61, s61, 0
	s_add_u32 s72, s72, 0x200
	s_addc_u32 s73, s73, 0
	s_add_u32 s76, s76, 0x200
	s_addc_u32 s77, s77, 0
	s_cmpk_eq_i32 s96, 0x4000
	s_waitcnt vmcnt(0) lgkmcnt(0)
; __device__ __forceinline__ void preproc_phase(Frame& F, int layer, int b, int cu_lo, int ncu) {
;     ...
;             for (int c = 0; c < 4; ++c) {
;                 f32x4 wiv = *(const f32x4*)(wi + (size_t)(cc + c) * 4), wfv = *(const f32x4*)(wf + (size_t)(cc + c) * 4);
; #pragma unroll
;                 for (int a = 0; a < 4; ++a)
; #pragma unroll
;                     for (int hh = 0; hh < 4; ++hh) { ai[a][hh] += q[a][c] * wiv[hh]; af[a][hh] += q[a][c] * wfv[hh]; }
;                 wiv = *(const f32x4*)(wi + (size_t)(1024 + cc + c) * 4); wfv = *(const f32x4*)(wf + (size_t)(1024 + cc + c) * 4);
; #pragma unroll
;                 for (int a = 0; a < 4; ++a)
; #pragma unroll
;                     for (int hh = 0; hh < 4; ++hh) { ai[a][hh] += k[a][c] * wiv[hh]; af[a][hh] += k[a][c] * wfv[hh]; }
;                 wiv = *(const f32x4*)(wi + (size_t)(2048 + cc + c) * 4); wfv = *(const f32x4*)(wf + (size_t)(2048 + cc + c) * 4);
; #pragma unroll
;                 for (int a = 0; a < 4; ++a)
; #pragma unroll
;                     for (int hh = 0; hh < 4; ++hh) { ai[a][hh] += v[a][c] * wiv[hh]; af[a][hh] += v[a][c] * wfv[hh]; }
;             }
	v_fmac_f32_e32 v120, v130, v194
	v_fmac_f32_e32 v121, v130, v195
	v_fmac_f32_e32 v112, v140, v194
	v_fmac_f32_e32 v113, v140, v195
	v_fmac_f32_e32 v104, v174, v194
	v_fmac_f32_e32 v105, v174, v195
	v_fmac_f32_e32 v96, v178, v194
	v_fmac_f32_e32 v97, v178, v195
	v_mul_f32_e32 v166, v138, v202
	v_mul_f32_e32 v167, v138, v203
	v_mul_f32_e32 v212, v170, v202
	v_mul_f32_e32 v213, v170, v203
	v_mul_f32_e32 v220, v190, v202
	v_mul_f32_e32 v221, v190, v203
	v_mul_f32_e32 v202, v186, v202
	v_mul_f32_e32 v203, v186, v203
	v_pk_add_f32 v[120:121], v[120:121], v[166:167]
	v_pk_add_f32 v[112:113], v[112:113], v[212:213]
	v_pk_add_f32 v[104:105], v[104:105], v[220:221]
	v_pk_add_f32 v[96:97], v[96:97], v[202:203]
	v_pk_fma_f32 v[120:121], v[124:125], v[18:19], v[120:121] op_sel_hi:[0,1,1]
	v_pk_fma_f32 v[112:113], v[132:133], v[18:19], v[112:113] op_sel_hi:[0,1,1]
	v_pk_fma_f32 v[104:105], v[144:145], v[18:19], v[104:105] op_sel_hi:[0,1,1]
	v_pk_fma_f32 v[18:19], v[180:181], v[18:19], v[96:97] op_sel_hi:[0,1,1]
	v_pk_fma_f32 v[120:121], v[128:129], v[6:7], v[120:121] op_sel_hi:[0,1,1]
	v_pk_fma_f32 v[112:113], v[142:143], v[6:7], v[112:113] op_sel_hi:[0,1,1]
	v_pk_fma_f32 v[104:105], v[176:177], v[6:7], v[104:105] op_sel_hi:[0,1,1]
	v_pk_fma_f32 v[6:7], v[184:185], v[6:7], v[18:19] op_sel_hi:[0,1,1]
	v_pk_fma_f32 v[6:7], v[188:189], v[10:11], v[6:7] op_sel_hi:[0,1,1]
	v_pk_fma_f32 v[6:7], v[182:183], v[14:15], v[6:7] op_sel_hi:[0,1,1]
	v_pk_fma_f32 v[6:7], v[178:179], v[22:23], v[6:7] op_sel:[1,0,0]
	v_fmac_f32_e32 v118, v130, v198
	v_pk_fma_f32 v[6:7], v[186:187], v[70:71], v[6:7] op_sel:[1,0,0]
	v_fmac_f32_e32 v119, v130, v199
	v_pk_fma_f32 v[6:7], v[180:181], v[78:79], v[6:7] op_sel:[1,0,0]
	v_fmac_f32_e32 v110, v140, v198
	v_pk_fma_f32 v[6:7], v[184:185], v[26:27], v[6:7] op_sel:[1,0,0]
	v_fmac_f32_e32 v111, v140, v199
	v_fmac_f32_e32 v102, v174, v198
	v_fmac_f32_e32 v103, v174, v199
	v_fmac_f32_e32 v94, v178, v198
	v_fmac_f32_e32 v95, v178, v199
	v_mul_f32_e32 v198, v138, v206
	v_mul_f32_e32 v199, v138, v207
	v_mul_f32_e32 v214, v170, v206
	v_mul_f32_e32 v215, v170, v207
	v_mul_f32_e32 v222, v190, v206
	v_mul_f32_e32 v223, v190, v207
	v_mul_f32_e32 v206, v186, v206
	v_mul_f32_e32 v207, v186, v207
	v_pk_fma_f32 v[6:7], v[188:189], v[66:67], v[6:7] op_sel:[1,0,0]
	v_pk_add_f32 v[118:119], v[118:119], v[198:199]
	v_pk_add_f32 v[110:111], v[110:111], v[214:215]
	v_pk_add_f32 v[102:103], v[102:103], v[222:223]
	v_pk_fma_f32 v[96:97], v[182:183], v[74:75], v[6:7] op_sel:[1,0,0]
	v_pk_add_f32 v[6:7], v[94:95], v[206:207]
	v_pk_fma_f32 v[118:119], v[124:125], v[30:31], v[118:119] op_sel_hi:[0,1,1]
	v_pk_fma_f32 v[110:111], v[132:133], v[30:31], v[110:111] op_sel_hi:[0,1,1]
	v_pk_fma_f32 v[102:103], v[144:145], v[30:31], v[102:103] op_sel_hi:[0,1,1]
	v_pk_fma_f32 v[6:7], v[180:181], v[30:31], v[6:7] op_sel_hi:[0,1,1]
	v_pk_fma_f32 v[118:119], v[128:129], v[2:3], v[118:119] op_sel_hi:[0,1,1]
	v_pk_fma_f32 v[110:111], v[142:143], v[2:3], v[110:111] op_sel_hi:[0,1,1]
	v_pk_fma_f32 v[102:103], v[176:177], v[2:3], v[102:103] op_sel_hi:[0,1,1]
	v_pk_fma_f32 v[2:3], v[184:185], v[2:3], v[6:7] op_sel_hi:[0,1,1]
	v_pk_fma_f32 v[2:3], v[188:189], v[34:35], v[2:3] op_sel_hi:[0,1,1]
	v_pk_fma_f32 v[2:3], v[182:183], v[38:39], v[2:3] op_sel_hi:[0,1,1]
	v_pk_fma_f32 v[2:3], v[178:179], v[42:43], v[2:3] op_sel:[1,0,0]
	v_fmac_f32_e32 v116, v130, v196
	v_pk_fma_f32 v[2:3], v[186:187], v[46:47], v[2:3] op_sel:[1,0,0]
	v_fmac_f32_e32 v117, v130, v197
	v_pk_fma_f32 v[2:3], v[180:181], v[50:51], v[2:3] op_sel:[1,0,0]
	v_fmac_f32_e32 v108, v140, v196
	v_pk_fma_f32 v[2:3], v[184:185], v[54:55], v[2:3] op_sel:[1,0,0]
	v_fmac_f32_e32 v109, v140, v197
	v_fmac_f32_e32 v100, v174, v196
	v_fmac_f32_e32 v101, v174, v197
	v_fmac_f32_e32 v92, v178, v196
	v_fmac_f32_e32 v93, v178, v197
	v_mul_f32_e32 v196, v186, v204
	v_mul_f32_e32 v197, v186, v205
	v_pk_fma_f32 v[2:3], v[188:189], v[58:59], v[2:3] op_sel:[1,0,0]
	v_fmac_f32_e32 v114, v130, v200
	v_pk_fma_f32 v[94:95], v[182:183], v[62:63], v[2:3] op_sel:[1,0,0]
	v_pk_add_f32 v[2:3], v[92:93], v[196:197]
	v_fmac_f32_e32 v115, v130, v201
	v_pk_fma_f32 v[2:3], v[180:181], v[20:21], v[2:3] op_sel_hi:[0,1,1]
	v_pk_fma_f32 v[2:3], v[184:185], v[8:9], v[2:3] op_sel_hi:[0,1,1]
	v_pk_fma_f32 v[2:3], v[188:189], v[12:13], v[2:3] op_sel_hi:[0,1,1]
	v_pk_fma_f32 v[2:3], v[182:183], v[16:17], v[2:3] op_sel_hi:[0,1,1]
	v_pk_fma_f32 v[2:3], v[178:179], v[24:25], v[2:3] op_sel:[1,0,0]
	v_fmac_f32_e32 v106, v140, v200
	v_pk_fma_f32 v[2:3], v[186:187], v[72:73], v[2:3] op_sel:[1,0,0]
	v_fmac_f32_e32 v107, v140, v201
	v_pk_fma_f32 v[2:3], v[180:181], v[80:81], v[2:3] op_sel:[1,0,0]
	v_fmac_f32_e32 v98, v174, v200
	v_pk_fma_f32 v[2:3], v[184:185], v[28:29], v[2:3] op_sel:[1,0,0]
	v_fmac_f32_e32 v99, v174, v201
	v_fmac_f32_e32 v90, v178, v200
	v_fmac_f32_e32 v91, v178, v201
	v_mul_f32_e32 v200, v138, v204
	v_mul_f32_e32 v210, v138, v208
	v_mul_f32_e32 v201, v138, v205
	v_mul_f32_e32 v211, v138, v209
	v_mul_f32_e32 v216, v170, v204
	v_mul_f32_e32 v218, v170, v208
	v_mul_f32_e32 v217, v170, v205
	v_mul_f32_e32 v219, v170, v209
	v_mul_f32_e32 v242, v190, v204
	v_mul_f32_e32 v244, v190, v208
	v_mul_f32_e32 v243, v190, v205
	v_mul_f32_e32 v245, v190, v209
	v_mul_f32_e32 v194, v186, v208
	v_mul_f32_e32 v195, v186, v209
	v_pk_fma_f32 v[2:3], v[188:189], v[68:69], v[2:3] op_sel:[1,0,0]
	v_pk_add_f32 v[116:117], v[116:117], v[200:201]
	v_pk_add_f32 v[114:115], v[114:115], v[210:211]
	v_pk_add_f32 v[108:109], v[108:109], v[216:217]
	v_pk_add_f32 v[106:107], v[106:107], v[218:219]
	v_pk_add_f32 v[100:101], v[100:101], v[242:243]
	v_pk_add_f32 v[98:99], v[98:99], v[244:245]
; __device__ __forceinline__ void preproc_phase(Frame& F, int layer, int b, int cu_lo, int ncu) {
;     ...
;             for (int c = 0; c < 4; ++c) {
;                 f32x4 wiv = *(const f32x4*)(wi + (size_t)(cc + c) * 4), wfv = *(const f32x4*)(wf + (size_t)(cc + c) * 4);
; #pragma unroll
;                 for (int a = 0; a < 4; ++a)
; #pragma unroll
;                     for (int hh = 0; hh < 4; ++hh) { ai[a][hh] += q[a][c] * wiv[hh]; af[a][hh] += q[a][c] * wfv[hh]; }
;                 wiv = *(const f32x4*)(wi + (size_t)(1024 + cc + c) * 4); wfv = *(const f32x4*)(wf + (size_t)(1024 + cc + c) * 4);
; #pragma unroll
;                 for (int a = 0; a < 4; ++a)
; #pragma unroll
;                     for (int hh = 0; hh < 4; ++hh) { ai[a][hh] += k[a][c] * wiv[hh]; af[a][hh] += k[a][c] * wfv[hh]; }
;                 wiv = *(const f32x4*)(wi + (size_t)(2048 + cc + c) * 4); wfv = *(const f32x4*)(wf + (size_t)(2048 + cc + c) * 4);
; #pragma unroll
;                 for (int a = 0; a < 4; ++a)
; #pragma unroll
;                     for (int hh = 0; hh < 4; ++hh) { ai[a][hh] += v[a][c] * wiv[hh]; af[a][hh] += v[a][c] * wfv[hh]; }
;             }
	v_pk_fma_f32 v[92:93], v[182:183], v[76:77], v[2:3] op_sel:[1,0,0]
	v_pk_add_f32 v[2:3], v[90:91], v[194:195]
	v_pk_fma_f32 v[116:117], v[124:125], v[20:21], v[116:117] op_sel_hi:[0,1,1]
	v_pk_fma_f32 v[114:115], v[124:125], v[32:33], v[114:115] op_sel_hi:[0,1,1]
	v_pk_fma_f32 v[108:109], v[132:133], v[20:21], v[108:109] op_sel_hi:[0,1,1]
	v_pk_fma_f32 v[106:107], v[132:133], v[32:33], v[106:107] op_sel_hi:[0,1,1]
	v_pk_fma_f32 v[100:101], v[144:145], v[20:21], v[100:101] op_sel_hi:[0,1,1]
	v_pk_fma_f32 v[98:99], v[144:145], v[32:33], v[98:99] op_sel_hi:[0,1,1]
	v_pk_fma_f32 v[2:3], v[180:181], v[32:33], v[2:3] op_sel_hi:[0,1,1]
	v_pk_fma_f32 v[116:117], v[128:129], v[8:9], v[116:117] op_sel_hi:[0,1,1]
	v_pk_fma_f32 v[114:115], v[128:129], v[4:5], v[114:115] op_sel_hi:[0,1,1]
	v_pk_fma_f32 v[108:109], v[142:143], v[8:9], v[108:109] op_sel_hi:[0,1,1]
	v_pk_fma_f32 v[106:107], v[142:143], v[4:5], v[106:107] op_sel_hi:[0,1,1]
	v_pk_fma_f32 v[100:101], v[176:177], v[8:9], v[100:101] op_sel_hi:[0,1,1]
	v_pk_fma_f32 v[98:99], v[176:177], v[4:5], v[98:99] op_sel_hi:[0,1,1]
	v_pk_fma_f32 v[2:3], v[184:185], v[4:5], v[2:3] op_sel_hi:[0,1,1]
	v_pk_fma_f32 v[120:121], v[136:137], v[10:11], v[120:121] op_sel_hi:[0,1,1]
	v_pk_fma_f32 v[118:119], v[136:137], v[34:35], v[118:119] op_sel_hi:[0,1,1]
	v_pk_fma_f32 v[116:117], v[136:137], v[12:13], v[116:117] op_sel_hi:[0,1,1]
	v_pk_fma_f32 v[114:115], v[136:137], v[36:37], v[114:115] op_sel_hi:[0,1,1]
	v_pk_fma_f32 v[112:113], v[172:173], v[10:11], v[112:113] op_sel_hi:[0,1,1]
	v_pk_fma_f32 v[110:111], v[172:173], v[34:35], v[110:111] op_sel_hi:[0,1,1]
	v_pk_fma_f32 v[108:109], v[172:173], v[12:13], v[108:109] op_sel_hi:[0,1,1]
	v_pk_fma_f32 v[106:107], v[172:173], v[36:37], v[106:107] op_sel_hi:[0,1,1]
	v_pk_fma_f32 v[104:105], v[192:193], v[10:11], v[104:105] op_sel_hi:[0,1,1]
	v_pk_fma_f32 v[102:103], v[192:193], v[34:35], v[102:103] op_sel_hi:[0,1,1]
	v_pk_fma_f32 v[100:101], v[192:193], v[12:13], v[100:101] op_sel_hi:[0,1,1]
	v_pk_fma_f32 v[98:99], v[192:193], v[36:37], v[98:99] op_sel_hi:[0,1,1]
	v_pk_fma_f32 v[2:3], v[188:189], v[36:37], v[2:3] op_sel_hi:[0,1,1]
	v_pk_fma_f32 v[120:121], v[126:127], v[14:15], v[120:121] op_sel_hi:[0,1,1]
	v_pk_fma_f32 v[118:119], v[126:127], v[38:39], v[118:119] op_sel_hi:[0,1,1]
	v_pk_fma_f32 v[116:117], v[126:127], v[16:17], v[116:117] op_sel_hi:[0,1,1]
	v_pk_fma_f32 v[114:115], v[126:127], v[40:41], v[114:115] op_sel_hi:[0,1,1]
	v_pk_fma_f32 v[112:113], v[134:135], v[14:15], v[112:113] op_sel_hi:[0,1,1]
	v_pk_fma_f32 v[110:111], v[134:135], v[38:39], v[110:111] op_sel_hi:[0,1,1]
	v_pk_fma_f32 v[108:109], v[134:135], v[16:17], v[108:109] op_sel_hi:[0,1,1]
	v_pk_fma_f32 v[106:107], v[134:135], v[40:41], v[106:107] op_sel_hi:[0,1,1]
	v_pk_fma_f32 v[104:105], v[148:149], v[14:15], v[104:105] op_sel_hi:[0,1,1]
	v_pk_fma_f32 v[102:103], v[148:149], v[38:39], v[102:103] op_sel_hi:[0,1,1]
	v_pk_fma_f32 v[100:101], v[148:149], v[16:17], v[100:101] op_sel_hi:[0,1,1]
	v_pk_fma_f32 v[98:99], v[148:149], v[40:41], v[98:99] op_sel_hi:[0,1,1]
	v_pk_fma_f32 v[2:3], v[182:183], v[40:41], v[2:3] op_sel_hi:[0,1,1]
	v_pk_fma_f32 v[120:121], v[130:131], v[22:23], v[120:121] op_sel:[1,0,0]
	v_pk_fma_f32 v[118:119], v[130:131], v[42:43], v[118:119] op_sel:[1,0,0]
	v_pk_fma_f32 v[116:117], v[130:131], v[24:25], v[116:117] op_sel:[1,0,0]
	v_pk_fma_f32 v[114:115], v[130:131], v[44:45], v[114:115] op_sel:[1,0,0]
	v_pk_fma_f32 v[112:113], v[140:141], v[22:23], v[112:113] op_sel:[1,0,0]
	v_pk_fma_f32 v[110:111], v[140:141], v[42:43], v[110:111] op_sel:[1,0,0]
	v_pk_fma_f32 v[108:109], v[140:141], v[24:25], v[108:109] op_sel:[1,0,0]
	v_pk_fma_f32 v[106:107], v[140:141], v[44:45], v[106:107] op_sel:[1,0,0]
	v_pk_fma_f32 v[104:105], v[174:175], v[22:23], v[104:105] op_sel:[1,0,0]
	v_pk_fma_f32 v[102:103], v[174:175], v[42:43], v[102:103] op_sel:[1,0,0]
	v_pk_fma_f32 v[100:101], v[174:175], v[24:25], v[100:101] op_sel:[1,0,0]
	v_pk_fma_f32 v[98:99], v[174:175], v[44:45], v[98:99] op_sel:[1,0,0]
	v_pk_fma_f32 v[2:3], v[178:179], v[44:45], v[2:3] op_sel:[1,0,0]
	v_pk_fma_f32 v[120:121], v[138:139], v[70:71], v[120:121] op_sel:[1,0,0]
	v_pk_fma_f32 v[118:119], v[138:139], v[46:47], v[118:119] op_sel:[1,0,0]
	v_pk_fma_f32 v[116:117], v[138:139], v[72:73], v[116:117] op_sel:[1,0,0]
	v_pk_fma_f32 v[114:115], v[138:139], v[48:49], v[114:115] op_sel:[1,0,0]
	v_pk_fma_f32 v[112:113], v[170:171], v[70:71], v[112:113] op_sel:[1,0,0]
	v_pk_fma_f32 v[110:111], v[170:171], v[46:47], v[110:111] op_sel:[1,0,0]
	v_pk_fma_f32 v[108:109], v[170:171], v[72:73], v[108:109] op_sel:[1,0,0]
	v_pk_fma_f32 v[106:107], v[170:171], v[48:49], v[106:107] op_sel:[1,0,0]
	v_pk_fma_f32 v[104:105], v[190:191], v[70:71], v[104:105] op_sel:[1,0,0]
	v_pk_fma_f32 v[102:103], v[190:191], v[46:47], v[102:103] op_sel:[1,0,0]
	v_pk_fma_f32 v[100:101], v[190:191], v[72:73], v[100:101] op_sel:[1,0,0]
	v_pk_fma_f32 v[98:99], v[190:191], v[48:49], v[98:99] op_sel:[1,0,0]
	v_pk_fma_f32 v[2:3], v[186:187], v[48:49], v[2:3] op_sel:[1,0,0]
	v_pk_fma_f32 v[120:121], v[124:125], v[78:79], v[120:121] op_sel:[1,0,0]
	v_pk_fma_f32 v[118:119], v[124:125], v[50:51], v[118:119] op_sel:[1,0,0]
	v_pk_fma_f32 v[116:117], v[124:125], v[80:81], v[116:117] op_sel:[1,0,0]
	v_pk_fma_f32 v[114:115], v[124:125], v[52:53], v[114:115] op_sel:[1,0,0]
	v_pk_fma_f32 v[112:113], v[132:133], v[78:79], v[112:113] op_sel:[1,0,0]
	v_pk_fma_f32 v[110:111], v[132:133], v[50:51], v[110:111] op_sel:[1,0,0]
	v_pk_fma_f32 v[108:109], v[132:133], v[80:81], v[108:109] op_sel:[1,0,0]
	v_pk_fma_f32 v[106:107], v[132:133], v[52:53], v[106:107] op_sel:[1,0,0]
; __device__ __forceinline__ void preproc_phase(Frame& F, int layer, int b, int cu_lo, int ncu) {
;     ...
;             float xm[7][4];
; #pragma unroll
;             for (int r = 0; r < 7; ++r) { const int t = t0 - 3 + r;
;                 if (t >= 0) { const u32x2 w = *(const u32x2*)(proj + (size_t)t * NP + C_MX + cc); xm[r][0] = bflo(w.x); xm[r][1] = bfhi(w.x); xm[r][2] = bflo(w.y); xm[r][3] = bfhi(w.y); }
;                 else { xm[r][0] = xm[r][1] = xm[r][2] = xm[r][3] = 0.f; } }
;     ...
;             for (int c = 0; c < 4; ++c) {
;                 f32x4 wiv = *(const f32x4*)(wi + (size_t)(cc + c) * 4), wfv = *(const f32x4*)(wf + (size_t)(cc + c) * 4);
; #pragma unroll
;                 for (int a = 0; a < 4; ++a)
; #pragma unroll
;                     for (int hh = 0; hh < 4; ++hh) { ai[a][hh] += q[a][c] * wiv[hh]; af[a][hh] += q[a][c] * wfv[hh]; }
;                 wiv = *(const f32x4*)(wi + (size_t)(1024 + cc + c) * 4); wfv = *(const f32x4*)(wf + (size_t)(1024 + cc + c) * 4);
; #pragma unroll
;                 for (int a = 0; a < 4; ++a)
; #pragma unroll
;                     for (int hh = 0; hh < 4; ++hh) { ai[a][hh] += k[a][c] * wiv[hh]; af[a][hh] += k[a][c] * wfv[hh]; }
;                 wiv = *(const f32x4*)(wi + (size_t)(2048 + cc + c) * 4); wfv = *(const f32x4*)(wf + (size_t)(2048 + cc + c) * 4);
; #pragma unroll
;                 for (int a = 0; a < 4; ++a)
; #pragma unroll
;                     for (int hh = 0; hh < 4; ++hh) { ai[a][hh] += v[a][c] * wiv[hh]; af[a][hh] += v[a][c] * wfv[hh]; }
;             }
	v_pk_fma_f32 v[104:105], v[144:145], v[78:79], v[104:105] op_sel:[1,0,0]
	v_pk_fma_f32 v[102:103], v[144:145], v[50:51], v[102:103] op_sel:[1,0,0]
	v_pk_fma_f32 v[100:101], v[144:145], v[80:81], v[100:101] op_sel:[1,0,0]
	v_pk_fma_f32 v[98:99], v[144:145], v[52:53], v[98:99] op_sel:[1,0,0]
	v_pk_fma_f32 v[2:3], v[180:181], v[52:53], v[2:3] op_sel:[1,0,0]
	v_pk_fma_f32 v[120:121], v[128:129], v[26:27], v[120:121] op_sel:[1,0,0]
	v_pk_fma_f32 v[118:119], v[128:129], v[54:55], v[118:119] op_sel:[1,0,0]
	v_pk_fma_f32 v[116:117], v[128:129], v[28:29], v[116:117] op_sel:[1,0,0]
	v_pk_fma_f32 v[114:115], v[128:129], v[56:57], v[114:115] op_sel:[1,0,0]
	v_pk_fma_f32 v[112:113], v[142:143], v[26:27], v[112:113] op_sel:[1,0,0]
	v_pk_fma_f32 v[110:111], v[142:143], v[54:55], v[110:111] op_sel:[1,0,0]
	v_pk_fma_f32 v[108:109], v[142:143], v[28:29], v[108:109] op_sel:[1,0,0]
	v_pk_fma_f32 v[106:107], v[142:143], v[56:57], v[106:107] op_sel:[1,0,0]
	v_pk_fma_f32 v[104:105], v[176:177], v[26:27], v[104:105] op_sel:[1,0,0]
	v_pk_fma_f32 v[102:103], v[176:177], v[54:55], v[102:103] op_sel:[1,0,0]
	v_pk_fma_f32 v[100:101], v[176:177], v[28:29], v[100:101] op_sel:[1,0,0]
	v_pk_fma_f32 v[98:99], v[176:177], v[56:57], v[98:99] op_sel:[1,0,0]
	v_pk_fma_f32 v[2:3], v[184:185], v[56:57], v[2:3] op_sel:[1,0,0]
	v_pk_fma_f32 v[120:121], v[136:137], v[66:67], v[120:121] op_sel:[1,0,0]
	v_pk_fma_f32 v[118:119], v[136:137], v[58:59], v[118:119] op_sel:[1,0,0]
	v_pk_fma_f32 v[116:117], v[136:137], v[68:69], v[116:117] op_sel:[1,0,0]
	v_pk_fma_f32 v[114:115], v[136:137], v[60:61], v[114:115] op_sel:[1,0,0]
	v_pk_fma_f32 v[112:113], v[172:173], v[66:67], v[112:113] op_sel:[1,0,0]
	v_pk_fma_f32 v[110:111], v[172:173], v[58:59], v[110:111] op_sel:[1,0,0]
	v_pk_fma_f32 v[108:109], v[172:173], v[68:69], v[108:109] op_sel:[1,0,0]
	v_pk_fma_f32 v[106:107], v[172:173], v[60:61], v[106:107] op_sel:[1,0,0]
	v_pk_fma_f32 v[104:105], v[192:193], v[66:67], v[104:105] op_sel:[1,0,0]
	v_pk_fma_f32 v[102:103], v[192:193], v[58:59], v[102:103] op_sel:[1,0,0]
	v_pk_fma_f32 v[100:101], v[192:193], v[68:69], v[100:101] op_sel:[1,0,0]
	v_pk_fma_f32 v[98:99], v[192:193], v[60:61], v[98:99] op_sel:[1,0,0]
	v_pk_fma_f32 v[2:3], v[188:189], v[60:61], v[2:3] op_sel:[1,0,0]
	v_pk_fma_f32 v[120:121], v[126:127], v[74:75], v[120:121] op_sel:[1,0,0]
	v_pk_fma_f32 v[118:119], v[126:127], v[62:63], v[118:119] op_sel:[1,0,0]
	v_pk_fma_f32 v[116:117], v[126:127], v[76:77], v[116:117] op_sel:[1,0,0]
	v_pk_fma_f32 v[114:115], v[126:127], v[64:65], v[114:115] op_sel:[1,0,0]
	v_pk_fma_f32 v[112:113], v[134:135], v[74:75], v[112:113] op_sel:[1,0,0]
	v_pk_fma_f32 v[110:111], v[134:135], v[62:63], v[110:111] op_sel:[1,0,0]
	v_pk_fma_f32 v[108:109], v[134:135], v[76:77], v[108:109] op_sel:[1,0,0]
	v_pk_fma_f32 v[106:107], v[134:135], v[64:65], v[106:107] op_sel:[1,0,0]
	v_pk_fma_f32 v[104:105], v[148:149], v[74:75], v[104:105] op_sel:[1,0,0]
	v_pk_fma_f32 v[102:103], v[148:149], v[62:63], v[102:103] op_sel:[1,0,0]
	v_pk_fma_f32 v[100:101], v[148:149], v[76:77], v[100:101] op_sel:[1,0,0]
	v_pk_fma_f32 v[98:99], v[148:149], v[64:65], v[98:99] op_sel:[1,0,0]
	v_pk_fma_f32 v[90:91], v[182:183], v[64:65], v[2:3] op_sel:[1,0,0]
	s_cbranch_scc1 .LBB0_313
.LBB0_299:
	v_mov_b32_e32 v2, s78
	v_mov_b32_e32 v6, s66
	v_readfirstlane_b32 s0, v2
	v_mov_b32_e32 v2, s33
	v_mov_b32_e32 v10, s67
	v_mov_b32_e32 v14, s80
	s_waitcnt lgkmcnt(0)
	ds_read2_b64 v[2:5], v2 offset1:1
	ds_read2_b64 v[6:9], v6 offset1:1
	ds_read2_b64 v[10:13], v10 offset1:1
	ds_read_b64 v[14:15], v14
	v_mov_b32_e32 v190, 0
	v_mov_b32_e32 v191, 0
	v_mov_b32_e32 v192, 0
	v_mov_b32_e32 v193, 0
	v_mov_b32_e32 v194, 0
	v_mov_b32_e32 v195, 0
	v_mov_b32_e32 v196, 0
	v_mov_b32_e32 v197, 0
	v_mov_b32_e32 v198, 0
	v_mov_b32_e32 v199, 0
	v_mov_b32_e32 v200, 0
	v_mov_b32_e32 v201, 0
	v_mov_b32_e32 v202, 0
	v_mov_b32_e32 v203, 0
	s_andn2_b64 vcc, exec, s[90:91]
	s_cbranch_vccnz .Lxm_skipA_a
	v_lshl_add_u64 v[16:17], s[76:77], 0, v[0:1]
	global_load_dwordx2 v[190:191], v[16:17], off
	v_lshl_add_u64 v[16:17], s[72:73], 0, v[0:1]
	global_load_dwordx2 v[192:193], v[16:17], off
	v_lshl_add_u64 v[16:17], s[60:61], 0, v[0:1]
	global_load_dwordx2 v[194:195], v[16:17], off
.Lxm_skipA_a:
	s_andn2_b64 vcc, exec, s[94:95]
	s_cbranch_vccnz .Lxm_skipB_a
	v_lshl_add_u64 v[16:17], s[52:53], 0, v[0:1]
	global_load_dwordx2 v[196:197], v[16:17], off
	v_lshl_add_u64 v[16:17], s[42:43], 0, v[0:1]
	global_load_dwordx2 v[198:199], v[16:17], off
	v_lshl_add_u64 v[16:17], s[40:41], 0, v[0:1]
	global_load_dwordx2 v[200:201], v[16:17], off
	v_lshl_add_u64 v[16:17], s[38:39], 0, v[0:1]
	global_load_dwordx2 v[202:203], v[16:17], off
.Lxm_skipB_a:
	v_cndmask_b32_e64 v16, 0, 1, s[94:95]
	v_cmp_ne_u32_e64 s[10:11], 1, v16
	s_nop 1
	s_and_b64 vcc, exec, s[10:11]
	s_branch .LBB0_298
; __device__ __forceinline__ void preproc_phase(Frame& F, int layer, int b, int cu_lo, int ncu) {
;     ...
; #pragma unroll
;         for (int a = 0; a < 4; ++a)
; #pragma unroll
;             for (int hh = 0; hh < 4; ++hh) { ai[a][hh] = wave_sum(ai[a][hh]); af[a][hh] = wave_sum(af[a][hh]); }
.LBB0_313:
	ds_bpermute_b32 v6, v235, v121
	ds_bpermute_b32 v7, v235, v119
	ds_bpermute_b32 v10, v235, v116
	ds_bpermute_b32 v2, v235, v120
	ds_bpermute_b32 v3, v235, v118
	s_waitcnt lgkmcnt(4)
	v_add_f32_e32 v6, v121, v6
	ds_bpermute_b32 v8, v236, v6
	s_waitcnt lgkmcnt(4)
	v_add_f32_e32 v7, v119, v7
	ds_bpermute_b32 v9, v236, v7
	s_waitcnt lgkmcnt(4)
	v_add_f32_e32 v10, v116, v10
	ds_bpermute_b32 v11, v236, v10
	s_waitcnt lgkmcnt(2)
	v_add_f32_e32 v6, v6, v8
	ds_bpermute_b32 v8, v237, v6
	s_waitcnt lgkmcnt(2)
	v_add_f32_e32 v7, v7, v9
	ds_bpermute_b32 v9, v237, v7
	s_waitcnt lgkmcnt(2)
	v_add_f32_e32 v10, v10, v11
	ds_bpermute_b32 v11, v237, v10
	s_waitcnt lgkmcnt(2)
	v_add_f32_e32 v6, v6, v8
	ds_bpermute_b32 v8, v238, v6
	s_waitcnt lgkmcnt(2)
	v_add_f32_e32 v7, v7, v9
	ds_bpermute_b32 v9, v238, v7
	v_add_f32_e32 v2, v120, v2
	v_add_f32_e32 v3, v118, v3
	s_waitcnt lgkmcnt(1)
	v_add_f32_e32 v6, v6, v8
	ds_bpermute_b32 v8, v239, v6
	s_waitcnt lgkmcnt(1)
	v_add_f32_e32 v9, v7, v9
	ds_bpermute_b32 v12, v239, v9
	ds_bpermute_b32 v4, v236, v2
	ds_bpermute_b32 v5, v236, v3
	s_waitcnt lgkmcnt(3)
	v_add_f32_e32 v6, v6, v8
	ds_bpermute_b32 v8, v235, v114
	s_waitcnt lgkmcnt(3)
	v_add_f32_e32 v36, v9, v12
	v_add_f32_e32 v9, v10, v11
	ds_bpermute_b32 v10, v238, v9
	ds_bpermute_b32 v12, v235, v117
	s_waitcnt lgkmcnt(2)
	v_add_f32_e32 v8, v114, v8
	ds_bpermute_b32 v13, v236, v8
	v_add_f32_e32 v2, v2, v4
	s_waitcnt lgkmcnt(2)
	v_add_f32_e32 v9, v9, v10
	ds_bpermute_b32 v10, v239, v9
	s_waitcnt lgkmcnt(2)
	v_add_f32_e32 v12, v117, v12
	s_waitcnt lgkmcnt(1)
	v_add_f32_e32 v8, v8, v13
	ds_bpermute_b32 v11, v237, v8
	ds_bpermute_b32 v13, v236, v12
	s_waitcnt lgkmcnt(2)
	v_add_f32_e32 v35, v9, v10
	ds_bpermute_b32 v9, v235, v115
	v_add_f32_e32 v3, v3, v5
	s_waitcnt lgkmcnt(2)
	v_add_f32_e32 v8, v8, v11
	ds_bpermute_b32 v11, v238, v8
	ds_bpermute_b32 v4, v237, v2
	s_waitcnt lgkmcnt(2)
	v_add_f32_e32 v9, v115, v9
	ds_bpermute_b32 v5, v237, v3
	ds_bpermute_b32 v7, v240, v6
	s_waitcnt lgkmcnt(3)
	v_add_f32_e32 v8, v8, v11
	v_add_f32_e32 v11, v12, v13
	ds_bpermute_b32 v10, v239, v8
	ds_bpermute_b32 v12, v237, v11
	ds_bpermute_b32 v13, v236, v9
	s_waitcnt lgkmcnt(5)
	v_add_f32_e32 v2, v2, v4
	s_waitcnt lgkmcnt(4)
	v_add_f32_e32 v3, v3, v5
	s_waitcnt lgkmcnt(2)
	v_add_f32_e32 v34, v8, v10
	s_waitcnt lgkmcnt(1)
	v_add_f32_e32 v8, v11, v12
	ds_bpermute_b32 v10, v238, v8
	s_waitcnt lgkmcnt(1)
	v_add_f32_e32 v9, v9, v13
	ds_bpermute_b32 v11, v237, v9
	ds_bpermute_b32 v12, v235, v112
	ds_bpermute_b32 v4, v238, v2
	s_waitcnt lgkmcnt(3)
	v_add_f32_e32 v8, v8, v10
	ds_bpermute_b32 v10, v239, v8
	s_waitcnt lgkmcnt(3)
	v_add_f32_e32 v9, v9, v11
	s_waitcnt lgkmcnt(2)
	v_add_f32_e32 v12, v112, v12
	ds_bpermute_b32 v11, v238, v9
	ds_bpermute_b32 v13, v236, v12
	s_waitcnt lgkmcnt(2)
	v_add_f32_e32 v33, v8, v10
	ds_bpermute_b32 v8, v235, v110
	ds_bpermute_b32 v5, v238, v3
	s_waitcnt lgkmcnt(3)
	v_add_f32_e32 v9, v9, v11
	s_waitcnt lgkmcnt(2)
	v_add_f32_e32 v11, v12, v13
	ds_bpermute_b32 v10, v239, v9
	ds_bpermute_b32 v12, v237, v11
	s_waitcnt lgkmcnt(3)
	v_add_f32_e32 v8, v110, v8
	ds_bpermute_b32 v13, v236, v8
	v_add_f32_e32 v2, v2, v4
	s_waitcnt lgkmcnt(2)
	v_add_f32_e32 v32, v9, v10
	s_waitcnt lgkmcnt(1)
	v_add_f32_e32 v9, v11, v12
	ds_bpermute_b32 v10, v238, v9
	s_waitcnt lgkmcnt(1)
	v_add_f32_e32 v8, v8, v13
	ds_bpermute_b32 v11, v237, v8
	ds_bpermute_b32 v12, v235, v113
	v_add_f32_e32 v3, v3, v5
	s_waitcnt lgkmcnt(2)
	v_add_f32_e32 v9, v9, v10
	ds_bpermute_b32 v10, v239, v9
	s_waitcnt lgkmcnt(2)
	v_add_f32_e32 v8, v8, v11
	s_waitcnt lgkmcnt(1)
	v_add_f32_e32 v12, v113, v12
	ds_bpermute_b32 v11, v238, v8
	ds_bpermute_b32 v13, v236, v12
	s_waitcnt lgkmcnt(2)
	v_add_f32_e32 v31, v9, v10
	ds_bpermute_b32 v9, v235, v111
	ds_bpermute_b32 v4, v239, v2
	s_waitcnt lgkmcnt(3)
	v_add_f32_e32 v8, v8, v11
	s_waitcnt lgkmcnt(2)
	v_add_f32_e32 v11, v12, v13
	ds_bpermute_b32 v10, v239, v8
	ds_bpermute_b32 v12, v237, v11
	s_waitcnt lgkmcnt(3)
	v_add_f32_e32 v9, v111, v9
	ds_bpermute_b32 v13, v236, v9
	ds_bpermute_b32 v5, v239, v3
	s_waitcnt lgkmcnt(3)
	v_add_f32_e32 v30, v8, v10
	s_waitcnt lgkmcnt(2)
	v_add_f32_e32 v8, v11, v12
	ds_bpermute_b32 v10, v238, v8
	s_waitcnt lgkmcnt(2)
	v_add_f32_e32 v9, v9, v13
	ds_bpermute_b32 v11, v237, v9
	ds_bpermute_b32 v12, v235, v108
	v_add_f32_e32 v2, v2, v4
	s_waitcnt lgkmcnt(2)
	v_add_f32_e32 v8, v8, v10
	ds_bpermute_b32 v10, v239, v8
	s_waitcnt lgkmcnt(2)
	v_add_f32_e32 v9, v9, v11
	s_waitcnt lgkmcnt(1)
	v_add_f32_e32 v12, v108, v12
	ds_bpermute_b32 v11, v238, v9
	ds_bpermute_b32 v13, v236, v12
	s_waitcnt lgkmcnt(2)
	v_add_f32_e32 v29, v8, v10
	ds_bpermute_b32 v8, v235, v106
	v_add_f32_e32 v4, v3, v5
	s_waitcnt lgkmcnt(2)
	v_add_f32_e32 v9, v9, v11
	s_waitcnt lgkmcnt(1)
	v_add_f32_e32 v11, v12, v13
	ds_bpermute_b32 v10, v239, v9
	ds_bpermute_b32 v12, v237, v11
	s_waitcnt lgkmcnt(2)
	v_add_f32_e32 v8, v106, v8
	ds_bpermute_b32 v13, v236, v8
	ds_bpermute_b32 v3, v240, v2
	s_waitcnt lgkmcnt(3)
	v_add_f32_e32 v28, v9, v10
	s_waitcnt lgkmcnt(2)
	v_add_f32_e32 v9, v11, v12
	ds_bpermute_b32 v10, v238, v9
	s_waitcnt lgkmcnt(2)
	v_add_f32_e32 v8, v8, v13
	ds_bpermute_b32 v11, v237, v8
	ds_bpermute_b32 v12, v235, v109
	ds_bpermute_b32 v5, v240, v4
	s_waitcnt lgkmcnt(3)
	v_add_f32_e32 v9, v9, v10
	ds_bpermute_b32 v10, v239, v9
	s_waitcnt lgkmcnt(3)
	v_add_f32_e32 v8, v8, v11
	s_waitcnt lgkmcnt(2)
	v_add_f32_e32 v12, v109, v12
	ds_bpermute_b32 v11, v238, v8
	ds_bpermute_b32 v13, v236, v12
	s_waitcnt lgkmcnt(2)
	v_add_f32_e32 v27, v9, v10
	ds_bpermute_b32 v9, v235, v107
	ds_bpermute_b32 v37, v240, v36
	s_waitcnt lgkmcnt(3)
	v_add_f32_e32 v8, v8, v11
	s_waitcnt lgkmcnt(2)
; __device__ __forceinline__ void preproc_phase(Frame& F, int layer, int b, int cu_lo, int ncu) {
;     ...
; #pragma unroll
;         for (int a = 0; a < 4; ++a)
; #pragma unroll
;             for (int hh = 0; hh < 4; ++hh) { ai[a][hh] = wave_sum(ai[a][hh]); af[a][hh] = wave_sum(af[a][hh]); }
	v_add_f32_e32 v11, v12, v13
	ds_bpermute_b32 v10, v239, v8
	ds_bpermute_b32 v12, v237, v11
	s_waitcnt lgkmcnt(3)
	v_add_f32_e32 v9, v107, v9
	ds_bpermute_b32 v13, v236, v9
	ds_bpermute_b32 v38, v240, v35
	s_waitcnt lgkmcnt(3)
	v_add_f32_e32 v26, v8, v10
	s_waitcnt lgkmcnt(2)
	v_add_f32_e32 v8, v11, v12
	ds_bpermute_b32 v10, v238, v8
	s_waitcnt lgkmcnt(2)
	v_add_f32_e32 v9, v9, v13
	ds_bpermute_b32 v11, v237, v9
	ds_bpermute_b32 v12, v235, v104
	ds_bpermute_b32 v39, v240, v34
	s_waitcnt lgkmcnt(3)
	v_add_f32_e32 v8, v8, v10
	ds_bpermute_b32 v10, v239, v8
	s_waitcnt lgkmcnt(3)
	v_add_f32_e32 v9, v9, v11
	s_waitcnt lgkmcnt(2)
	v_add_f32_e32 v12, v104, v12
	ds_bpermute_b32 v11, v238, v9
	ds_bpermute_b32 v13, v236, v12
	s_waitcnt lgkmcnt(2)
	v_add_f32_e32 v25, v8, v10
	ds_bpermute_b32 v8, v235, v102
	ds_bpermute_b32 v40, v240, v33
	s_waitcnt lgkmcnt(3)
	v_add_f32_e32 v9, v9, v11
	s_waitcnt lgkmcnt(2)
	v_add_f32_e32 v11, v12, v13
	ds_bpermute_b32 v10, v239, v9
	ds_bpermute_b32 v12, v237, v11
	s_waitcnt lgkmcnt(3)
	v_add_f32_e32 v8, v102, v8
	ds_bpermute_b32 v13, v236, v8
	ds_bpermute_b32 v41, v240, v32
	s_waitcnt lgkmcnt(3)
	v_add_f32_e32 v24, v9, v10
	s_waitcnt lgkmcnt(2)
	v_add_f32_e32 v9, v11, v12
	ds_bpermute_b32 v10, v238, v9
	s_waitcnt lgkmcnt(2)
	v_add_f32_e32 v8, v8, v13
	ds_bpermute_b32 v11, v237, v8
	ds_bpermute_b32 v12, v235, v105
	ds_bpermute_b32 v42, v240, v31
	s_waitcnt lgkmcnt(3)
	v_add_f32_e32 v9, v9, v10
	ds_bpermute_b32 v10, v239, v9
	s_waitcnt lgkmcnt(3)
	v_add_f32_e32 v8, v8, v11
	s_waitcnt lgkmcnt(2)
	v_add_f32_e32 v12, v105, v12
	ds_bpermute_b32 v11, v238, v8
	ds_bpermute_b32 v13, v236, v12
	s_waitcnt lgkmcnt(2)
	v_add_f32_e32 v23, v9, v10
	ds_bpermute_b32 v9, v235, v103
	ds_bpermute_b32 v43, v240, v30
	s_waitcnt lgkmcnt(3)
	v_add_f32_e32 v8, v8, v11
	s_waitcnt lgkmcnt(2)
	v_add_f32_e32 v11, v12, v13
	ds_bpermute_b32 v10, v239, v8
	ds_bpermute_b32 v12, v237, v11
	s_waitcnt lgkmcnt(3)
	v_add_f32_e32 v9, v103, v9
	ds_bpermute_b32 v13, v236, v9
	ds_bpermute_b32 v44, v240, v29
	s_waitcnt lgkmcnt(3)
	v_add_f32_e32 v22, v8, v10
	s_waitcnt lgkmcnt(2)
	v_add_f32_e32 v8, v11, v12
	ds_bpermute_b32 v10, v238, v8
	s_waitcnt lgkmcnt(2)
	v_add_f32_e32 v9, v9, v13
	ds_bpermute_b32 v11, v237, v9
	ds_bpermute_b32 v12, v235, v100
	ds_bpermute_b32 v45, v240, v28
	s_waitcnt lgkmcnt(3)
	v_add_f32_e32 v8, v8, v10
	ds_bpermute_b32 v10, v239, v8
	s_waitcnt lgkmcnt(3)
	v_add_f32_e32 v9, v9, v11
	s_waitcnt lgkmcnt(2)
	v_add_f32_e32 v12, v100, v12
	ds_bpermute_b32 v11, v238, v9
	ds_bpermute_b32 v13, v236, v12
	s_waitcnt lgkmcnt(2)
	v_add_f32_e32 v21, v8, v10
	ds_bpermute_b32 v8, v235, v98
	ds_bpermute_b32 v46, v240, v27
	s_waitcnt lgkmcnt(3)
	v_add_f32_e32 v9, v9, v11
	s_waitcnt lgkmcnt(2)
	v_add_f32_e32 v11, v12, v13
	ds_bpermute_b32 v10, v239, v9
	ds_bpermute_b32 v12, v237, v11
	s_waitcnt lgkmcnt(3)
	v_add_f32_e32 v8, v98, v8
	ds_bpermute_b32 v13, v236, v8
	ds_bpermute_b32 v47, v240, v26
	s_waitcnt lgkmcnt(3)
	v_add_f32_e32 v20, v9, v10
	s_waitcnt lgkmcnt(2)
	v_add_f32_e32 v9, v11, v12
	ds_bpermute_b32 v10, v238, v9
	s_waitcnt lgkmcnt(2)
	v_add_f32_e32 v8, v8, v13
	ds_bpermute_b32 v11, v237, v8
	ds_bpermute_b32 v12, v235, v101
	ds_bpermute_b32 v48, v240, v25
	s_waitcnt lgkmcnt(3)
	v_add_f32_e32 v9, v9, v10
	ds_bpermute_b32 v10, v239, v9
	s_waitcnt lgkmcnt(3)
	v_add_f32_e32 v8, v8, v11
	s_waitcnt lgkmcnt(2)
	v_add_f32_e32 v12, v101, v12
	ds_bpermute_b32 v11, v238, v8
	ds_bpermute_b32 v13, v236, v12
	s_waitcnt lgkmcnt(2)
	v_add_f32_e32 v19, v9, v10
	ds_bpermute_b32 v9, v235, v99
	ds_bpermute_b32 v49, v240, v24
	s_waitcnt lgkmcnt(3)
	v_add_f32_e32 v8, v8, v11
	s_waitcnt lgkmcnt(2)
	v_add_f32_e32 v11, v12, v13
	ds_bpermute_b32 v10, v239, v8
	ds_bpermute_b32 v12, v237, v11
	s_waitcnt lgkmcnt(3)
	v_add_f32_e32 v9, v99, v9
	ds_bpermute_b32 v13, v236, v9
	ds_bpermute_b32 v50, v240, v23
	s_waitcnt lgkmcnt(3)
	v_add_f32_e32 v18, v8, v10
	s_waitcnt lgkmcnt(2)
	v_add_f32_e32 v8, v11, v12
	ds_bpermute_b32 v10, v238, v8
	s_waitcnt lgkmcnt(2)
	v_add_f32_e32 v9, v9, v13
	ds_bpermute_b32 v11, v237, v9
	ds_bpermute_b32 v12, v235, v96
	ds_bpermute_b32 v51, v240, v22
	s_waitcnt lgkmcnt(3)
	v_add_f32_e32 v8, v8, v10
	ds_bpermute_b32 v10, v239, v8
	s_waitcnt lgkmcnt(3)
	v_add_f32_e32 v9, v9, v11
	s_waitcnt lgkmcnt(2)
	v_add_f32_e32 v12, v96, v12
	ds_bpermute_b32 v11, v238, v9
	ds_bpermute_b32 v13, v236, v12
	s_waitcnt lgkmcnt(2)
	v_add_f32_e32 v17, v8, v10
	ds_bpermute_b32 v8, v235, v94
	ds_bpermute_b32 v52, v240, v21
	s_waitcnt lgkmcnt(3)
	v_add_f32_e32 v9, v9, v11
	s_waitcnt lgkmcnt(2)
	v_add_f32_e32 v11, v12, v13
	ds_bpermute_b32 v10, v239, v9
	ds_bpermute_b32 v12, v237, v11
	s_waitcnt lgkmcnt(3)
	v_add_f32_e32 v8, v94, v8
	ds_bpermute_b32 v13, v236, v8
	ds_bpermute_b32 v53, v240, v20
	s_waitcnt lgkmcnt(3)
	v_add_f32_e32 v16, v9, v10
	s_waitcnt lgkmcnt(2)
	v_add_f32_e32 v9, v11, v12
	ds_bpermute_b32 v10, v238, v9
	s_waitcnt lgkmcnt(2)
	v_add_f32_e32 v8, v8, v13
	ds_bpermute_b32 v12, v235, v97
	ds_bpermute_b32 v11, v237, v8
	ds_bpermute_b32 v54, v240, v19
	s_waitcnt lgkmcnt(3)
	v_add_f32_e32 v9, v9, v10
	ds_bpermute_b32 v10, v239, v9
	s_waitcnt lgkmcnt(3)
	v_add_f32_e32 v12, v97, v12
	s_waitcnt lgkmcnt(2)
	v_add_f32_e32 v8, v8, v11
	ds_bpermute_b32 v13, v236, v12
	ds_bpermute_b32 v11, v238, v8
	s_waitcnt lgkmcnt(2)
	v_add_f32_e32 v15, v9, v10
	ds_bpermute_b32 v9, v235, v95
	ds_bpermute_b32 v55, v240, v18
	s_waitcnt lgkmcnt(3)
	v_add_f32_e32 v10, v12, v13
	s_waitcnt lgkmcnt(2)
	v_add_f32_e32 v8, v8, v11
	ds_bpermute_b32 v11, v237, v10
	ds_bpermute_b32 v12, v235, v92
	s_waitcnt lgkmcnt(3)
	v_add_f32_e32 v9, v95, v9
	ds_bpermute_b32 v13, v239, v8
	ds_bpermute_b32 v14, v236, v9
	s_waitcnt lgkmcnt(3)
; __device__ __forceinline__ float logsigmoidf_(float x) { return fminf(x, 0.f) - log1pf(__expf(-fabsf(x))); }
; __device__ __forceinline__ void preproc_phase(Frame& F, int layer, int b, int cu_lo, int ncu) {
;     ...
;             for (int hh = 0; hh < 4; ++hh) { ai[a][hh] = wave_sum(ai[a][hh]); af[a][hh] = wave_sum(af[a][hh]); }
;         if (F.lane == 0) {
; #pragma unroll
;             for (int a = 0; a < 4; ++a)
; #pragma unroll
;                 for (int hh = 0; hh < 4; ++hh) { MG[(size_t)(t0 + a) * 8 + hh] = ai[a][hh] + INP(I_M_B_I)[layer * 4 + hh]; MG[(size_t)(t0 + a) * 8 + 4 + hh] = logsigmoidf_(af[a][hh] + INP(I_M_B_F)[layer * 4 + hh]); }
	v_add_f32_e32 v10, v10, v11
	s_waitcnt lgkmcnt(2)
	v_add_f32_e32 v11, v92, v12
	ds_bpermute_b32 v12, v236, v11
	ds_bpermute_b32 v59, v238, v10
	s_waitcnt lgkmcnt(2)
	v_add_f32_e32 v9, v9, v14
	v_add_f32_e32 v14, v8, v13
	ds_bpermute_b32 v60, v237, v9
	s_waitcnt lgkmcnt(2)
	v_add_f32_e32 v8, v11, v12
	ds_bpermute_b32 v11, v237, v8
	s_waitcnt lgkmcnt(2)
	v_add_f32_e32 v10, v10, v59
	ds_bpermute_b32 v13, v239, v10
	s_waitcnt lgkmcnt(2)
	v_add_f32_e32 v9, v9, v60
	ds_bpermute_b32 v12, v238, v9
	s_waitcnt lgkmcnt(2)
	v_add_f32_e32 v8, v8, v11
	ds_bpermute_b32 v11, v238, v8
	s_waitcnt lgkmcnt(2)
	v_add_f32_e32 v13, v10, v13
	ds_bpermute_b32 v56, v240, v17
	s_waitcnt lgkmcnt(2)
	v_add_f32_e32 v9, v9, v12
	ds_bpermute_b32 v12, v239, v9
	s_waitcnt lgkmcnt(2)
	v_add_f32_e32 v8, v8, v11
	ds_bpermute_b32 v10, v239, v8
	ds_bpermute_b32 v57, v240, v16
	ds_bpermute_b32 v58, v240, v15
	s_waitcnt lgkmcnt(3)
	v_add_f32_e32 v12, v9, v12
	ds_bpermute_b32 v9, v235, v90
	s_waitcnt lgkmcnt(3)
	v_add_f32_e32 v11, v8, v10
	ds_bpermute_b32 v8, v235, v93
	ds_bpermute_b32 v10, v235, v91
	ds_bpermute_b32 v59, v240, v14
	s_waitcnt lgkmcnt(3)
	v_add_f32_e32 v9, v90, v9
	ds_bpermute_b32 v63, v236, v9
	s_waitcnt lgkmcnt(3)
	v_add_f32_e32 v8, v93, v8
	s_waitcnt lgkmcnt(2)
	v_add_f32_e32 v10, v91, v10
	ds_bpermute_b32 v64, v236, v8
	ds_bpermute_b32 v65, v236, v10
	s_waitcnt lgkmcnt(2)
	v_add_f32_e32 v9, v9, v63
	ds_bpermute_b32 v63, v237, v9
	ds_bpermute_b32 v60, v240, v13
	s_waitcnt lgkmcnt(3)
	v_add_f32_e32 v8, v8, v64
	s_waitcnt lgkmcnt(2)
	v_add_f32_e32 v10, v10, v65
	ds_bpermute_b32 v64, v237, v8
	ds_bpermute_b32 v65, v237, v10
	s_waitcnt lgkmcnt(3)
	v_add_f32_e32 v9, v9, v63
	ds_bpermute_b32 v63, v238, v9
	ds_bpermute_b32 v61, v240, v12
	s_waitcnt lgkmcnt(3)
	v_add_f32_e32 v8, v8, v64
	s_waitcnt lgkmcnt(2)
	v_add_f32_e32 v10, v10, v65
	ds_bpermute_b32 v64, v238, v8
	ds_bpermute_b32 v65, v238, v10
	s_waitcnt lgkmcnt(3)
	v_add_f32_e32 v9, v9, v63
	ds_bpermute_b32 v63, v239, v9
	ds_bpermute_b32 v62, v240, v11
	s_waitcnt lgkmcnt(3)
	v_add_f32_e32 v8, v8, v64
	s_waitcnt lgkmcnt(2)
	v_add_f32_e32 v65, v10, v65
	ds_bpermute_b32 v64, v239, v8
	ds_bpermute_b32 v66, v239, v65
	s_waitcnt lgkmcnt(3)
	v_add_f32_e32 v10, v9, v63
	ds_bpermute_b32 v63, v240, v10
	s_waitcnt lgkmcnt(2)
	v_add_f32_e32 v9, v8, v64
	s_waitcnt lgkmcnt(1)
	v_add_f32_e32 v8, v65, v66
	ds_bpermute_b32 v64, v240, v9
	ds_bpermute_b32 v65, v240, v8
	s_mov_b64 s[10:11], exec
	v_readlane_b32 s0, v253, 31
	v_add_f32_e32 v36, v36, v37
	v_add_f32_e32 v37, v6, v7
	v_add_f32_e32 v6, v2, v3
	v_mov_b32_e32 v2, s0
	ds_read_b64 v[2:3], v2
	v_readlane_b32 s0, v253, 32
	v_add_f32_e32 v35, v35, v38
	v_add_f32_e32 v38, v4, v5
	v_mov_b32_e32 v4, s0
	s_lshl_b64 s[0:1], s[26:27], 5
	v_readlane_b32 s4, v254, 27
	s_add_u32 s0, s49, s0
	v_readlane_b32 s5, v254, 28
	s_addc_u32 s1, s54, s1
	s_lshl_b64 s[4:5], s[4:5], 2
	ds_read_b64 v[4:5], v4
	s_waitcnt lgkmcnt(1)
	v_lshl_add_u64 v[2:3], v[2:3], 0, s[4:5]
	flat_load_dword v7, v[2:3]
	v_add_f32_e32 v34, v34, v39
	v_add_f32_e32 v31, v31, v42
	s_waitcnt lgkmcnt(0)
	v_lshl_add_u64 v[4:5], v[4:5], 0, s[4:5]
	global_load_dword v110, v[2:3], off
	global_load_dword v111, v[2:3], off offset:4
	global_load_dword v112, v[2:3], off offset:8
	global_load_dword v113, v[2:3], off offset:12
	global_load_dword v114, v[4:5], off
	global_load_dword v115, v[4:5], off offset:4
	global_load_dword v116, v[4:5], off offset:8
	global_load_dword v117, v[4:5], off offset:12
	v_add_f32_e32 v33, v33, v40
	v_add_f32_e32 v32, v32, v41
	v_add_f32_e32 v30, v30, v43
	s_mov_b32 s4, 0x3f2aaaab
	v_add_f32_e32 v29, v29, v44
	v_add_f32_e32 v28, v28, v45
	v_add_f32_e32 v27, v27, v46
	v_add_f32_e32 v26, v26, v47
	v_add_f32_e32 v25, v25, v48
	v_add_f32_e32 v24, v24, v49
	v_add_f32_e32 v23, v23, v50
	s_mov_b32 s5, 0x3f317218
	s_mov_b32 s13, 0x33800000
	v_add_f32_e32 v22, v22, v51
	v_add_f32_e32 v21, v21, v52
	v_add_f32_e32 v20, v20, v53
	v_add_f32_e32 v19, v19, v54
	v_add_f32_e32 v18, v18, v55
	v_add_f32_e32 v17, v17, v56
	v_add_f32_e32 v16, v16, v57
	v_add_f32_e32 v15, v15, v58
	v_add_f32_e32 v14, v14, v59
	v_add_f32_e32 v13, v13, v60
	v_add_f32_e32 v12, v12, v61
	v_add_f32_e32 v11, v11, v62
	v_add_f32_e32 v10, v10, v63
	v_add_f32_e32 v9, v9, v64
	v_add_f32_e32 v8, v8, v65
	s_waitcnt vmcnt(0)
; __device__ __forceinline__ float logsigmoidf_(float x) { return fminf(x, 0.f) - log1pf(__expf(-fabsf(x))); }
; __device__ __forceinline__ void preproc_phase(Frame& F, int layer, int b, int cu_lo, int ncu) {
;     ...
;         if (F.lane == 0) {
; #pragma unroll
;             for (int a = 0; a < 4; ++a)
; #pragma unroll
;                 for (int hh = 0; hh < 4; ++hh) { MG[(size_t)(t0 + a) * 8 + hh] = ai[a][hh] + INP(I_M_B_I)[layer * 4 + hh]; MG[(size_t)(t0 + a) * 8 + 4 + hh] = logsigmoidf_(af[a][hh] + INP(I_M_B_F)[layer * 4 + hh]); }
	s_mov_b64 exec, 0x1
	v_mov_b32_e32 v118, v6
	v_mov_b32_e32 v119, v38
	s_mov_b64 exec, 0x2
	v_mov_b32_e32 v118, v37
	v_mov_b32_e32 v119, v36
	s_mov_b64 exec, 0x4
	v_mov_b32_e32 v118, v35
	v_mov_b32_e32 v119, v34
	s_mov_b64 exec, 0x8
	v_mov_b32_e32 v118, v33
	v_mov_b32_e32 v119, v32
	s_mov_b64 exec, 0x10
	v_mov_b32_e32 v118, v31
	v_mov_b32_e32 v119, v30
	s_mov_b64 exec, 0x20
	v_mov_b32_e32 v118, v29
	v_mov_b32_e32 v119, v28
	s_mov_b64 exec, 0x40
	v_mov_b32_e32 v118, v27
	v_mov_b32_e32 v119, v26
	s_mov_b64 exec, 0x80
	v_mov_b32_e32 v118, v25
	v_mov_b32_e32 v119, v24
	s_mov_b64 exec, 0x100
	v_mov_b32_e32 v118, v23
	v_mov_b32_e32 v119, v22
	s_mov_b64 exec, 0x200
	v_mov_b32_e32 v118, v21
	v_mov_b32_e32 v119, v20
	s_mov_b64 exec, 0x400
	v_mov_b32_e32 v118, v19
	v_mov_b32_e32 v119, v18
	s_mov_b64 exec, 0x800
	v_mov_b32_e32 v118, v17
	v_mov_b32_e32 v119, v16
	s_mov_b64 exec, 0x1000
	v_mov_b32_e32 v118, v15
	v_mov_b32_e32 v119, v14
	s_mov_b64 exec, 0x2000
	v_mov_b32_e32 v118, v13
	v_mov_b32_e32 v119, v12
	s_mov_b64 exec, 0x4000
	v_mov_b32_e32 v118, v11
	v_mov_b32_e32 v119, v10
	s_mov_b64 exec, 0x8000
	v_mov_b32_e32 v118, v9
	v_mov_b32_e32 v119, v8
	s_mov_b64 exec, 0x1111
	v_mov_b32_e32 v120, v7
	v_mov_b32_e32 v121, v114
	s_mov_b64 exec, 0x2222
	v_mov_b32_e32 v120, v111
	v_mov_b32_e32 v121, v115
	s_mov_b64 exec, 0x4444
	v_mov_b32_e32 v120, v112
	v_mov_b32_e32 v121, v116
	s_mov_b64 exec, 0x8888
	v_mov_b32_e32 v120, v113
	v_mov_b32_e32 v121, v117
	s_mov_b64 exec, 0xffff
	v_add_f32_e32 v122, v118, v120
	v_add_f32_e32 v39, v119, v121
	v_min_f32_e32 v38, 0, v39
	v_mul_f32_e64 v39, |v39|, s65
	v_exp_f32_e32 v39, v39
	s_nop 0
	v_add_f32_e32 v42, 1.0, v39
	v_add_f32_e32 v40, -1.0, v42
	v_sub_f32_e32 v41, v40, v42
	v_add_f32_e32 v41, 1.0, v41
	v_sub_f32_e32 v40, v39, v40
	v_add_f32_e32 v43, v40, v41
	v_frexp_mant_f32_e32 v40, v42
	v_cmp_gt_f32_e32 vcc, s4, v40
	v_cvt_f64_f32_e32 v[40:41], v42
	v_frexp_exp_i32_f64_e32 v40, v[40:41]
	v_subbrev_co_u32_e32 v40, vcc, 0, v40, vcc
	v_sub_u32_e32 v41, 0, v40
	v_ldexp_f32 v42, v42, v41
	v_ldexp_f32 v41, v43, v41
	v_add_f32_e32 v43, -1.0, v42
	v_add_f32_e32 v44, 1.0, v43
	v_sub_f32_e32 v44, v42, v44
	v_add_f32_e32 v44, v41, v44
	v_add_f32_e32 v45, v43, v44
	v_sub_f32_e32 v43, v45, v43
	v_sub_f32_e32 v43, v44, v43
	v_add_f32_e32 v44, 1.0, v42
	v_add_f32_e32 v46, -1.0, v44
	v_sub_f32_e32 v42, v42, v46
	v_add_f32_e32 v41, v41, v42
	v_add_f32_e32 v42, v44, v41
	v_sub_f32_e32 v44, v42, v44
	v_sub_f32_e32 v41, v41, v44
	v_rcp_f32_e32 v44, v42
	v_cvt_f32_i32_e32 v40, v40
	v_cmp_neq_f32_e32 vcc, s51, v39
	v_mul_f32_e32 v46, v45, v44
	v_mul_f32_e32 v47, v42, v46
	v_fma_f32 v48, v46, v42, -v47
	v_fmac_f32_e32 v48, v46, v41
	v_add_f32_e32 v49, v47, v48
	v_sub_f32_e32 v50, v45, v49
	v_sub_f32_e32 v45, v45, v50
	v_sub_f32_e32 v47, v49, v47
	v_sub_f32_e32 v45, v45, v49
	v_add_f32_e32 v43, v43, v45
	v_sub_f32_e32 v45, v47, v48
	v_add_f32_e32 v43, v45, v43
	v_add_f32_e32 v45, v50, v43
	v_mul_f32_e32 v47, v44, v45
	v_mul_f32_e32 v48, v42, v47
	v_fma_f32 v42, v47, v42, -v48
	v_fmac_f32_e32 v42, v47, v41
	v_sub_f32_e32 v41, v50, v45
	v_add_f32_e32 v41, v43, v41
	v_add_f32_e32 v43, v48, v42
	v_sub_f32_e32 v49, v45, v43
	v_sub_f32_e32 v45, v45, v49
	v_sub_f32_e32 v48, v43, v48
	v_sub_f32_e32 v43, v45, v43
	v_add_f32_e32 v41, v41, v43
	v_sub_f32_e32 v42, v48, v42
	v_add_f32_e32 v41, v42, v41
	v_add_f32_e32 v42, v46, v47
	v_add_f32_e32 v41, v49, v41
	v_sub_f32_e32 v43, v42, v46
	v_mul_f32_e32 v41, v44, v41
	v_sub_f32_e32 v43, v47, v43
	v_add_f32_e32 v41, v43, v41
	v_mul_f32_e32 v46, 0x3f317218, v40
	v_add_f32_e32 v43, v42, v41
	v_fma_f32 v47, v40, s5, -v46
	v_mul_f32_e32 v44, v43, v43
	v_fmac_f32_e32 v47, 0xb102e308, v40
	v_sub_f32_e32 v40, v43, v42
	v_fmamk_f32 v45, v44, 0x3e9b6dac, v226
	v_sub_f32_e32 v40, v41, v40
	v_add_f32_e32 v41, v46, v47
	v_fmaak_f32 v45, v44, v45, 0x3f2aaada
	v_sub_f32_e32 v42, v41, v46
	v_ldexp_f32 v46, v43, 1
	v_mul_f32_e32 v43, v43, v44
	v_mul_f32_e32 v43, v43, v45
	v_add_f32_e32 v44, v46, v43
	v_sub_f32_e32 v45, v44, v46
	v_ldexp_f32 v40, v40, 1
	v_sub_f32_e32 v43, v43, v45
	v_add_f32_e32 v40, v40, v43
	v_add_f32_e32 v43, v44, v40
	v_sub_f32_e32 v44, v43, v44
	v_sub_f32_e32 v40, v40, v44
	v_add_f32_e32 v44, v41, v43
	v_sub_f32_e32 v45, v44, v41
	v_sub_f32_e32 v46, v44, v45
	v_sub_f32_e32 v42, v47, v42
	v_sub_f32_e32 v41, v41, v46
	v_sub_f32_e32 v43, v43, v45
	v_add_f32_e32 v41, v43, v41
	v_add_f32_e32 v43, v42, v40
	v_sub_f32_e32 v45, v43, v42
	v_sub_f32_e32 v46, v43, v45
	v_sub_f32_e32 v42, v42, v46
	v_sub_f32_e32 v40, v40, v45
	v_add_f32_e32 v41, v43, v41
	v_add_f32_e32 v40, v40, v42
	v_add_f32_e32 v42, v44, v41
	v_sub_f32_e32 v43, v42, v44
	v_sub_f32_e32 v41, v41, v43
	v_add_f32_e32 v40, v40, v41
	v_add_f32_e32 v40, v42, v40
	v_cndmask_b32_e32 v40, v227, v40, vcc
	v_cmp_ngt_f32_e32 vcc, -1.0, v39
	s_nop 1
	v_cndmask_b32_e32 v40, v228, v40, vcc
	v_cmp_neq_f32_e32 vcc, -1.0, v39
	s_nop 1
	v_cndmask_b32_e32 v40, v229, v40, vcc
	v_cmp_lt_f32_e64 vcc, |v39|, s13
	s_nop 1
	v_cndmask_b32_e32 v39, v40, v39, vcc
	v_sub_f32_e32 v38, v38, v39
	v_lshrrev_b32_e32 v123, 2, v225
	v_and_b32_e32 v124, 3, v225
	v_lshlrev_b32_e32 v123, 5, v123
	v_lshl_or_b32 v123, v124, 2, v123
	global_store_dword v123, v122, s[0:1]
	global_store_dword v123, v38, s[0:1] offset:16
	s_branch .LBB0_294

; __device__ __forceinline__ void preproc_phase(Frame& F, int layer, int b, int cu_lo, int ncu) {
;     ...
; #pragma unroll
;         for (int a = 0; a < 4; ++a)
; #pragma unroll
;             for (int hh = 0; hh < 4; ++hh) { ai[a][hh] = wave_sum(ai[a][hh]); af[a][hh] = wave_sum(af[a][hh]); }
.LBB0_341:
	ds_bpermute_b32 v6, v235, v121
	ds_bpermute_b32 v7, v235, v119
	ds_bpermute_b32 v10, v235, v116
	ds_bpermute_b32 v2, v235, v120
	ds_bpermute_b32 v3, v235, v118
	s_waitcnt lgkmcnt(4)
	v_add_f32_e32 v6, v121, v6
	ds_bpermute_b32 v8, v236, v6
	s_waitcnt lgkmcnt(4)
	v_add_f32_e32 v7, v119, v7
	ds_bpermute_b32 v9, v236, v7
	s_waitcnt lgkmcnt(4)
	v_add_f32_e32 v10, v116, v10
	ds_bpermute_b32 v11, v236, v10
	s_waitcnt lgkmcnt(2)
	v_add_f32_e32 v6, v6, v8
	ds_bpermute_b32 v8, v237, v6
	s_waitcnt lgkmcnt(2)
	v_add_f32_e32 v7, v7, v9
	ds_bpermute_b32 v9, v237, v7
	s_waitcnt lgkmcnt(2)
	v_add_f32_e32 v10, v10, v11
	ds_bpermute_b32 v11, v237, v10
	s_waitcnt lgkmcnt(2)
	v_add_f32_e32 v6, v6, v8
	ds_bpermute_b32 v8, v238, v6
	s_waitcnt lgkmcnt(2)
	v_add_f32_e32 v7, v7, v9
	ds_bpermute_b32 v9, v238, v7
	v_add_f32_e32 v2, v120, v2
	v_add_f32_e32 v3, v118, v3
	s_waitcnt lgkmcnt(1)
	v_add_f32_e32 v6, v6, v8
	ds_bpermute_b32 v8, v239, v6
	s_waitcnt lgkmcnt(1)
	v_add_f32_e32 v9, v7, v9
	ds_bpermute_b32 v12, v239, v9
	ds_bpermute_b32 v4, v236, v2
	ds_bpermute_b32 v5, v236, v3
	s_waitcnt lgkmcnt(3)
	v_add_f32_e32 v6, v6, v8
	ds_bpermute_b32 v8, v235, v114
	s_waitcnt lgkmcnt(3)
	v_add_f32_e32 v36, v9, v12
	v_add_f32_e32 v9, v10, v11
	ds_bpermute_b32 v10, v238, v9
	ds_bpermute_b32 v12, v235, v117
	s_waitcnt lgkmcnt(2)
	v_add_f32_e32 v8, v114, v8
	ds_bpermute_b32 v13, v236, v8
	v_add_f32_e32 v2, v2, v4
	s_waitcnt lgkmcnt(2)
	v_add_f32_e32 v9, v9, v10
	ds_bpermute_b32 v10, v239, v9
	s_waitcnt lgkmcnt(2)
	v_add_f32_e32 v12, v117, v12
	s_waitcnt lgkmcnt(1)
	v_add_f32_e32 v8, v8, v13
	ds_bpermute_b32 v11, v237, v8
	ds_bpermute_b32 v13, v236, v12
	s_waitcnt lgkmcnt(2)
	v_add_f32_e32 v35, v9, v10
	ds_bpermute_b32 v9, v235, v115
	v_add_f32_e32 v3, v3, v5
	s_waitcnt lgkmcnt(2)
	v_add_f32_e32 v8, v8, v11
	ds_bpermute_b32 v11, v238, v8
	ds_bpermute_b32 v4, v237, v2
	s_waitcnt lgkmcnt(2)
	v_add_f32_e32 v9, v115, v9
	ds_bpermute_b32 v5, v237, v3
	ds_bpermute_b32 v7, v240, v6
	s_waitcnt lgkmcnt(3)
	v_add_f32_e32 v8, v8, v11
	v_add_f32_e32 v11, v12, v13
	ds_bpermute_b32 v10, v239, v8
	ds_bpermute_b32 v12, v237, v11
	ds_bpermute_b32 v13, v236, v9
	s_waitcnt lgkmcnt(5)
	v_add_f32_e32 v2, v2, v4
	s_waitcnt lgkmcnt(4)
	v_add_f32_e32 v3, v3, v5
	s_waitcnt lgkmcnt(2)
	v_add_f32_e32 v34, v8, v10
	s_waitcnt lgkmcnt(1)
	v_add_f32_e32 v8, v11, v12
	ds_bpermute_b32 v10, v238, v8
	s_waitcnt lgkmcnt(1)
	v_add_f32_e32 v9, v9, v13
	ds_bpermute_b32 v11, v237, v9
	ds_bpermute_b32 v12, v235, v112
	ds_bpermute_b32 v4, v238, v2
	s_waitcnt lgkmcnt(3)
	v_add_f32_e32 v8, v8, v10
	ds_bpermute_b32 v10, v239, v8
	s_waitcnt lgkmcnt(3)
	v_add_f32_e32 v9, v9, v11
	s_waitcnt lgkmcnt(2)
	v_add_f32_e32 v12, v112, v12
	ds_bpermute_b32 v11, v238, v9
	ds_bpermute_b32 v13, v236, v12
	s_waitcnt lgkmcnt(2)
	v_add_f32_e32 v33, v8, v10
	ds_bpermute_b32 v8, v235, v110
	ds_bpermute_b32 v5, v238, v3
	s_waitcnt lgkmcnt(3)
	v_add_f32_e32 v9, v9, v11
	s_waitcnt lgkmcnt(2)
	v_add_f32_e32 v11, v12, v13
	ds_bpermute_b32 v10, v239, v9
	ds_bpermute_b32 v12, v237, v11
	s_waitcnt lgkmcnt(3)
	v_add_f32_e32 v8, v110, v8
	ds_bpermute_b32 v13, v236, v8
	v_add_f32_e32 v2, v2, v4
	s_waitcnt lgkmcnt(2)
	v_add_f32_e32 v32, v9, v10
	s_waitcnt lgkmcnt(1)
	v_add_f32_e32 v9, v11, v12
	ds_bpermute_b32 v10, v238, v9
	s_waitcnt lgkmcnt(1)
	v_add_f32_e32 v8, v8, v13
	ds_bpermute_b32 v11, v237, v8
	ds_bpermute_b32 v12, v235, v113
	v_add_f32_e32 v3, v3, v5
	s_waitcnt lgkmcnt(2)
	v_add_f32_e32 v9, v9, v10
	ds_bpermute_b32 v10, v239, v9
	s_waitcnt lgkmcnt(2)
	v_add_f32_e32 v8, v8, v11
	s_waitcnt lgkmcnt(1)
	v_add_f32_e32 v12, v113, v12
	ds_bpermute_b32 v11, v238, v8
	ds_bpermute_b32 v13, v236, v12
	s_waitcnt lgkmcnt(2)
	v_add_f32_e32 v31, v9, v10
	ds_bpermute_b32 v9, v235, v111
	ds_bpermute_b32 v4, v239, v2
	s_waitcnt lgkmcnt(3)
	v_add_f32_e32 v8, v8, v11
	s_waitcnt lgkmcnt(2)
	v_add_f32_e32 v11, v12, v13
	ds_bpermute_b32 v10, v239, v8
	ds_bpermute_b32 v12, v237, v11
	s_waitcnt lgkmcnt(3)
	v_add_f32_e32 v9, v111, v9
	ds_bpermute_b32 v13, v236, v9
	ds_bpermute_b32 v5, v239, v3
	s_waitcnt lgkmcnt(3)
	v_add_f32_e32 v30, v8, v10
	s_waitcnt lgkmcnt(2)
	v_add_f32_e32 v8, v11, v12
	ds_bpermute_b32 v10, v238, v8
	s_waitcnt lgkmcnt(2)
	v_add_f32_e32 v9, v9, v13
	ds_bpermute_b32 v11, v237, v9
	ds_bpermute_b32 v12, v235, v108
	v_add_f32_e32 v2, v2, v4
	s_waitcnt lgkmcnt(2)
	v_add_f32_e32 v8, v8, v10
	ds_bpermute_b32 v10, v239, v8
	s_waitcnt lgkmcnt(2)
	v_add_f32_e32 v9, v9, v11
	s_waitcnt lgkmcnt(1)
	v_add_f32_e32 v12, v108, v12
	ds_bpermute_b32 v11, v238, v9
	ds_bpermute_b32 v13, v236, v12
	s_waitcnt lgkmcnt(2)
	v_add_f32_e32 v29, v8, v10
	ds_bpermute_b32 v8, v235, v106
	v_add_f32_e32 v4, v3, v5
	s_waitcnt lgkmcnt(2)
	v_add_f32_e32 v9, v9, v11
	s_waitcnt lgkmcnt(1)
	v_add_f32_e32 v11, v12, v13
	ds_bpermute_b32 v10, v239, v9
	ds_bpermute_b32 v12, v237, v11
	s_waitcnt lgkmcnt(2)
	v_add_f32_e32 v8, v106, v8
	ds_bpermute_b32 v13, v236, v8
	ds_bpermute_b32 v3, v240, v2
	s_waitcnt lgkmcnt(3)
	v_add_f32_e32 v28, v9, v10
	s_waitcnt lgkmcnt(2)
	v_add_f32_e32 v9, v11, v12
	ds_bpermute_b32 v10, v238, v9
	s_waitcnt lgkmcnt(2)
	v_add_f32_e32 v8, v8, v13
	ds_bpermute_b32 v11, v237, v8
	ds_bpermute_b32 v12, v235, v109
	ds_bpermute_b32 v5, v240, v4
	s_waitcnt lgkmcnt(3)
	v_add_f32_e32 v9, v9, v10
	ds_bpermute_b32 v10, v239, v9
	s_waitcnt lgkmcnt(3)
	v_add_f32_e32 v8, v8, v11
	s_waitcnt lgkmcnt(2)
	v_add_f32_e32 v12, v109, v12
	ds_bpermute_b32 v11, v238, v8
	ds_bpermute_b32 v13, v236, v12
	s_waitcnt lgkmcnt(2)
	v_add_f32_e32 v27, v9, v10
	ds_bpermute_b32 v9, v235, v107
	ds_bpermute_b32 v37, v240, v36
	s_waitcnt lgkmcnt(3)
	v_add_f32_e32 v8, v8, v11
	s_waitcnt lgkmcnt(2)
; __device__ __forceinline__ void preproc_phase(Frame& F, int layer, int b, int cu_lo, int ncu) {
;     ...
; #pragma unroll
;         for (int a = 0; a < 4; ++a)
; #pragma unroll
;             for (int hh = 0; hh < 4; ++hh) { ai[a][hh] = wave_sum(ai[a][hh]); af[a][hh] = wave_sum(af[a][hh]); }
	v_add_f32_e32 v11, v12, v13
	ds_bpermute_b32 v10, v239, v8
	ds_bpermute_b32 v12, v237, v11
	s_waitcnt lgkmcnt(3)
	v_add_f32_e32 v9, v107, v9
	ds_bpermute_b32 v13, v236, v9
	ds_bpermute_b32 v38, v240, v35
	s_waitcnt lgkmcnt(3)
	v_add_f32_e32 v26, v8, v10
	s_waitcnt lgkmcnt(2)
	v_add_f32_e32 v8, v11, v12
	ds_bpermute_b32 v10, v238, v8
	s_waitcnt lgkmcnt(2)
	v_add_f32_e32 v9, v9, v13
	ds_bpermute_b32 v11, v237, v9
	ds_bpermute_b32 v12, v235, v104
	ds_bpermute_b32 v39, v240, v34
	s_waitcnt lgkmcnt(3)
	v_add_f32_e32 v8, v8, v10
	ds_bpermute_b32 v10, v239, v8
	s_waitcnt lgkmcnt(3)
	v_add_f32_e32 v9, v9, v11
	s_waitcnt lgkmcnt(2)
	v_add_f32_e32 v12, v104, v12
	ds_bpermute_b32 v11, v238, v9
	ds_bpermute_b32 v13, v236, v12
	s_waitcnt lgkmcnt(2)
	v_add_f32_e32 v25, v8, v10
	ds_bpermute_b32 v8, v235, v102
	ds_bpermute_b32 v40, v240, v33
	s_waitcnt lgkmcnt(3)
	v_add_f32_e32 v9, v9, v11
	s_waitcnt lgkmcnt(2)
	v_add_f32_e32 v11, v12, v13
	ds_bpermute_b32 v10, v239, v9
	ds_bpermute_b32 v12, v237, v11
	s_waitcnt lgkmcnt(3)
	v_add_f32_e32 v8, v102, v8
	ds_bpermute_b32 v13, v236, v8
	ds_bpermute_b32 v41, v240, v32
	s_waitcnt lgkmcnt(3)
	v_add_f32_e32 v24, v9, v10
	s_waitcnt lgkmcnt(2)
	v_add_f32_e32 v9, v11, v12
	ds_bpermute_b32 v10, v238, v9
	s_waitcnt lgkmcnt(2)
	v_add_f32_e32 v8, v8, v13
	ds_bpermute_b32 v11, v237, v8
	ds_bpermute_b32 v12, v235, v105
	ds_bpermute_b32 v42, v240, v31
	s_waitcnt lgkmcnt(3)
	v_add_f32_e32 v9, v9, v10
	ds_bpermute_b32 v10, v239, v9
	s_waitcnt lgkmcnt(3)
	v_add_f32_e32 v8, v8, v11
	s_waitcnt lgkmcnt(2)
	v_add_f32_e32 v12, v105, v12
	ds_bpermute_b32 v11, v238, v8
	ds_bpermute_b32 v13, v236, v12
	s_waitcnt lgkmcnt(2)
	v_add_f32_e32 v23, v9, v10
	ds_bpermute_b32 v9, v235, v103
	ds_bpermute_b32 v43, v240, v30
	s_waitcnt lgkmcnt(3)
	v_add_f32_e32 v8, v8, v11
	s_waitcnt lgkmcnt(2)
	v_add_f32_e32 v11, v12, v13
	ds_bpermute_b32 v10, v239, v8
	ds_bpermute_b32 v12, v237, v11
	s_waitcnt lgkmcnt(3)
	v_add_f32_e32 v9, v103, v9
	ds_bpermute_b32 v13, v236, v9
	ds_bpermute_b32 v44, v240, v29
	s_waitcnt lgkmcnt(3)
	v_add_f32_e32 v22, v8, v10
	s_waitcnt lgkmcnt(2)
	v_add_f32_e32 v8, v11, v12
	ds_bpermute_b32 v10, v238, v8
	s_waitcnt lgkmcnt(2)
	v_add_f32_e32 v9, v9, v13
	ds_bpermute_b32 v11, v237, v9
	ds_bpermute_b32 v12, v235, v100
	ds_bpermute_b32 v45, v240, v28
	s_waitcnt lgkmcnt(3)
	v_add_f32_e32 v8, v8, v10
	ds_bpermute_b32 v10, v239, v8
	s_waitcnt lgkmcnt(3)
	v_add_f32_e32 v9, v9, v11
	s_waitcnt lgkmcnt(2)
	v_add_f32_e32 v12, v100, v12
	ds_bpermute_b32 v11, v238, v9
	ds_bpermute_b32 v13, v236, v12
	s_waitcnt lgkmcnt(2)
	v_add_f32_e32 v21, v8, v10
	ds_bpermute_b32 v8, v235, v98
	ds_bpermute_b32 v46, v240, v27
	s_waitcnt lgkmcnt(3)
	v_add_f32_e32 v9, v9, v11
	s_waitcnt lgkmcnt(2)
	v_add_f32_e32 v11, v12, v13
	ds_bpermute_b32 v10, v239, v9
	ds_bpermute_b32 v12, v237, v11
	s_waitcnt lgkmcnt(3)
	v_add_f32_e32 v8, v98, v8
	ds_bpermute_b32 v13, v236, v8
	ds_bpermute_b32 v47, v240, v26
	s_waitcnt lgkmcnt(3)
	v_add_f32_e32 v20, v9, v10
	s_waitcnt lgkmcnt(2)
	v_add_f32_e32 v9, v11, v12
	ds_bpermute_b32 v10, v238, v9
	s_waitcnt lgkmcnt(2)
	v_add_f32_e32 v8, v8, v13
	ds_bpermute_b32 v11, v237, v8
	ds_bpermute_b32 v12, v235, v101
	ds_bpermute_b32 v48, v240, v25
	s_waitcnt lgkmcnt(3)
	v_add_f32_e32 v9, v9, v10
	ds_bpermute_b32 v10, v239, v9
	s_waitcnt lgkmcnt(3)
	v_add_f32_e32 v8, v8, v11
	s_waitcnt lgkmcnt(2)
	v_add_f32_e32 v12, v101, v12
	ds_bpermute_b32 v11, v238, v8
	ds_bpermute_b32 v13, v236, v12
	s_waitcnt lgkmcnt(2)
	v_add_f32_e32 v19, v9, v10
	ds_bpermute_b32 v9, v235, v99
	ds_bpermute_b32 v49, v240, v24
	s_waitcnt lgkmcnt(3)
	v_add_f32_e32 v8, v8, v11
	s_waitcnt lgkmcnt(2)
	v_add_f32_e32 v11, v12, v13
	ds_bpermute_b32 v10, v239, v8
	ds_bpermute_b32 v12, v237, v11
	s_waitcnt lgkmcnt(3)
	v_add_f32_e32 v9, v99, v9
	ds_bpermute_b32 v13, v236, v9
	ds_bpermute_b32 v50, v240, v23
	s_waitcnt lgkmcnt(3)
	v_add_f32_e32 v18, v8, v10
	s_waitcnt lgkmcnt(2)
	v_add_f32_e32 v8, v11, v12
	ds_bpermute_b32 v10, v238, v8
	s_waitcnt lgkmcnt(2)
	v_add_f32_e32 v9, v9, v13
	ds_bpermute_b32 v11, v237, v9
	ds_bpermute_b32 v12, v235, v96
	ds_bpermute_b32 v51, v240, v22
	s_waitcnt lgkmcnt(3)
	v_add_f32_e32 v8, v8, v10
	ds_bpermute_b32 v10, v239, v8
	s_waitcnt lgkmcnt(3)
	v_add_f32_e32 v9, v9, v11
	s_waitcnt lgkmcnt(2)
	v_add_f32_e32 v12, v96, v12
	ds_bpermute_b32 v11, v238, v9
	ds_bpermute_b32 v13, v236, v12
	s_waitcnt lgkmcnt(2)
	v_add_f32_e32 v17, v8, v10
	ds_bpermute_b32 v8, v235, v94
	ds_bpermute_b32 v52, v240, v21
	s_waitcnt lgkmcnt(3)
	v_add_f32_e32 v9, v9, v11
	s_waitcnt lgkmcnt(2)
	v_add_f32_e32 v11, v12, v13
	ds_bpermute_b32 v10, v239, v9
	ds_bpermute_b32 v12, v237, v11
	s_waitcnt lgkmcnt(3)
	v_add_f32_e32 v8, v94, v8
	ds_bpermute_b32 v13, v236, v8
	ds_bpermute_b32 v53, v240, v20
	s_waitcnt lgkmcnt(3)
	v_add_f32_e32 v16, v9, v10
	s_waitcnt lgkmcnt(2)
	v_add_f32_e32 v9, v11, v12
	ds_bpermute_b32 v10, v238, v9
	s_waitcnt lgkmcnt(2)
	v_add_f32_e32 v8, v8, v13
	ds_bpermute_b32 v12, v235, v97
	ds_bpermute_b32 v11, v237, v8
	ds_bpermute_b32 v54, v240, v19
	s_waitcnt lgkmcnt(3)
	v_add_f32_e32 v9, v9, v10
	ds_bpermute_b32 v10, v239, v9
	s_waitcnt lgkmcnt(3)
	v_add_f32_e32 v12, v97, v12
	s_waitcnt lgkmcnt(2)
	v_add_f32_e32 v8, v8, v11
	ds_bpermute_b32 v13, v236, v12
	ds_bpermute_b32 v11, v238, v8
	s_waitcnt lgkmcnt(2)
	v_add_f32_e32 v15, v9, v10
	ds_bpermute_b32 v9, v235, v95
	ds_bpermute_b32 v55, v240, v18
	s_waitcnt lgkmcnt(3)
	v_add_f32_e32 v10, v12, v13
	s_waitcnt lgkmcnt(2)
	v_add_f32_e32 v8, v8, v11
	ds_bpermute_b32 v11, v237, v10
	ds_bpermute_b32 v12, v235, v92
	s_waitcnt lgkmcnt(3)
	v_add_f32_e32 v9, v95, v9
	ds_bpermute_b32 v13, v239, v8
	ds_bpermute_b32 v14, v236, v9
	s_waitcnt lgkmcnt(3)
; __device__ __forceinline__ float logsigmoidf_(float x) { return fminf(x, 0.f) - log1pf(__expf(-fabsf(x))); }
; __device__ __forceinline__ void preproc_phase(Frame& F, int layer, int b, int cu_lo, int ncu) {
;     ...
;             for (int hh = 0; hh < 4; ++hh) { ai[a][hh] = wave_sum(ai[a][hh]); af[a][hh] = wave_sum(af[a][hh]); }
;         if (F.lane == 0) {
; #pragma unroll
;             for (int a = 0; a < 4; ++a)
; #pragma unroll
;                 for (int hh = 0; hh < 4; ++hh) { MG[(size_t)(t0 + a) * 8 + hh] = ai[a][hh] + INP(I_M_B_I)[layer * 4 + hh]; MG[(size_t)(t0 + a) * 8 + 4 + hh] = logsigmoidf_(af[a][hh] + INP(I_M_B_F)[layer * 4 + hh]); }
	v_add_f32_e32 v10, v10, v11
	s_waitcnt lgkmcnt(2)
	v_add_f32_e32 v11, v92, v12
	ds_bpermute_b32 v12, v236, v11
	ds_bpermute_b32 v59, v238, v10
	s_waitcnt lgkmcnt(2)
	v_add_f32_e32 v9, v9, v14
	v_add_f32_e32 v14, v8, v13
	ds_bpermute_b32 v60, v237, v9
	s_waitcnt lgkmcnt(2)
	v_add_f32_e32 v8, v11, v12
	ds_bpermute_b32 v11, v237, v8
	s_waitcnt lgkmcnt(2)
	v_add_f32_e32 v10, v10, v59
	ds_bpermute_b32 v13, v239, v10
	s_waitcnt lgkmcnt(2)
	v_add_f32_e32 v9, v9, v60
	ds_bpermute_b32 v12, v238, v9
	s_waitcnt lgkmcnt(2)
	v_add_f32_e32 v8, v8, v11
	ds_bpermute_b32 v11, v238, v8
	s_waitcnt lgkmcnt(2)
	v_add_f32_e32 v13, v10, v13
	ds_bpermute_b32 v56, v240, v17
	s_waitcnt lgkmcnt(2)
	v_add_f32_e32 v9, v9, v12
	ds_bpermute_b32 v12, v239, v9
	s_waitcnt lgkmcnt(2)
	v_add_f32_e32 v8, v8, v11
	ds_bpermute_b32 v10, v239, v8
	ds_bpermute_b32 v57, v240, v16
	ds_bpermute_b32 v58, v240, v15
	s_waitcnt lgkmcnt(3)
	v_add_f32_e32 v12, v9, v12
	ds_bpermute_b32 v9, v235, v90
	s_waitcnt lgkmcnt(3)
	v_add_f32_e32 v11, v8, v10
	ds_bpermute_b32 v8, v235, v93
	ds_bpermute_b32 v10, v235, v91
	ds_bpermute_b32 v59, v240, v14
	s_waitcnt lgkmcnt(3)
	v_add_f32_e32 v9, v90, v9
	ds_bpermute_b32 v63, v236, v9
	s_waitcnt lgkmcnt(3)
	v_add_f32_e32 v8, v93, v8
	s_waitcnt lgkmcnt(2)
	v_add_f32_e32 v10, v91, v10
	ds_bpermute_b32 v64, v236, v8
	ds_bpermute_b32 v65, v236, v10
	s_waitcnt lgkmcnt(2)
	v_add_f32_e32 v9, v9, v63
	ds_bpermute_b32 v63, v237, v9
	ds_bpermute_b32 v60, v240, v13
	s_waitcnt lgkmcnt(3)
	v_add_f32_e32 v8, v8, v64
	s_waitcnt lgkmcnt(2)
	v_add_f32_e32 v10, v10, v65
	ds_bpermute_b32 v64, v237, v8
	ds_bpermute_b32 v65, v237, v10
	s_waitcnt lgkmcnt(3)
	v_add_f32_e32 v9, v9, v63
	ds_bpermute_b32 v63, v238, v9
	ds_bpermute_b32 v61, v240, v12
	s_waitcnt lgkmcnt(3)
	v_add_f32_e32 v8, v8, v64
	s_waitcnt lgkmcnt(2)
	v_add_f32_e32 v10, v10, v65
	ds_bpermute_b32 v64, v238, v8
	ds_bpermute_b32 v65, v238, v10
	s_waitcnt lgkmcnt(3)
	v_add_f32_e32 v9, v9, v63
	ds_bpermute_b32 v63, v239, v9
	ds_bpermute_b32 v62, v240, v11
	s_waitcnt lgkmcnt(3)
	v_add_f32_e32 v8, v8, v64
	s_waitcnt lgkmcnt(2)
	v_add_f32_e32 v65, v10, v65
	ds_bpermute_b32 v64, v239, v8
	ds_bpermute_b32 v66, v239, v65
	s_waitcnt lgkmcnt(3)
	v_add_f32_e32 v10, v9, v63
	ds_bpermute_b32 v63, v240, v10
	s_waitcnt lgkmcnt(2)
	v_add_f32_e32 v9, v8, v64
	s_waitcnt lgkmcnt(1)
	v_add_f32_e32 v8, v65, v66
	ds_bpermute_b32 v64, v240, v9
	ds_bpermute_b32 v65, v240, v8
	s_mov_b64 s[10:11], exec
	v_readlane_b32 s0, v253, 31
	v_add_f32_e32 v36, v36, v37
	v_add_f32_e32 v37, v6, v7
	v_add_f32_e32 v6, v2, v3
	v_mov_b32_e32 v2, s0
	ds_read_b64 v[2:3], v2
	v_readlane_b32 s0, v253, 32
	v_add_f32_e32 v35, v35, v38
	v_add_f32_e32 v38, v4, v5
	v_mov_b32_e32 v4, s0
	s_lshl_b64 s[0:1], s[26:27], 5
	v_readlane_b32 s4, v254, 27
	s_add_u32 s0, s45, s0
	v_readlane_b32 s5, v254, 28
	s_addc_u32 s1, s49, s1
	s_lshl_b64 s[4:5], s[4:5], 2
	ds_read_b64 v[4:5], v4
	s_waitcnt lgkmcnt(1)
	v_lshl_add_u64 v[2:3], v[2:3], 0, s[4:5]
	flat_load_dword v7, v[2:3]
	v_add_f32_e32 v34, v34, v39
	v_add_f32_e32 v31, v31, v42
	s_waitcnt lgkmcnt(0)
	v_lshl_add_u64 v[4:5], v[4:5], 0, s[4:5]
	global_load_dword v110, v[2:3], off
	global_load_dword v111, v[2:3], off offset:4
	global_load_dword v112, v[2:3], off offset:8
	global_load_dword v113, v[2:3], off offset:12
	global_load_dword v114, v[4:5], off
	global_load_dword v115, v[4:5], off offset:4
	global_load_dword v116, v[4:5], off offset:8
	global_load_dword v117, v[4:5], off offset:12
	v_add_f32_e32 v33, v33, v40
	v_add_f32_e32 v32, v32, v41
	v_add_f32_e32 v30, v30, v43
	s_mov_b32 s4, 0x3f2aaaab
	v_add_f32_e32 v29, v29, v44
	v_add_f32_e32 v28, v28, v45
	v_add_f32_e32 v27, v27, v46
	v_add_f32_e32 v26, v26, v47
	v_add_f32_e32 v25, v25, v48
	v_add_f32_e32 v24, v24, v49
	v_add_f32_e32 v23, v23, v50
	s_mov_b32 s5, 0x3f317218
	s_mov_b32 s13, 0x33800000
	v_add_f32_e32 v22, v22, v51
	v_add_f32_e32 v21, v21, v52
	v_add_f32_e32 v20, v20, v53
	v_add_f32_e32 v19, v19, v54
	v_add_f32_e32 v18, v18, v55
	v_add_f32_e32 v17, v17, v56
	v_add_f32_e32 v16, v16, v57
	v_add_f32_e32 v15, v15, v58
	v_add_f32_e32 v14, v14, v59
	v_add_f32_e32 v13, v13, v60
	v_add_f32_e32 v12, v12, v61
	v_add_f32_e32 v11, v11, v62
	v_add_f32_e32 v10, v10, v63
	v_add_f32_e32 v9, v9, v64
	v_add_f32_e32 v8, v8, v65
	s_waitcnt vmcnt(0)
; __device__ __forceinline__ float logsigmoidf_(float x) { return fminf(x, 0.f) - log1pf(__expf(-fabsf(x))); }
; __device__ __forceinline__ void preproc_phase(Frame& F, int layer, int b, int cu_lo, int ncu) {
;     ...
;         if (F.lane == 0) {
; #pragma unroll
;             for (int a = 0; a < 4; ++a)
; #pragma unroll
;                 for (int hh = 0; hh < 4; ++hh) { MG[(size_t)(t0 + a) * 8 + hh] = ai[a][hh] + INP(I_M_B_I)[layer * 4 + hh]; MG[(size_t)(t0 + a) * 8 + 4 + hh] = logsigmoidf_(af[a][hh] + INP(I_M_B_F)[layer * 4 + hh]); }
	s_mov_b64 exec, 0x1
	v_mov_b32_e32 v118, v6
	v_mov_b32_e32 v119, v38
	s_mov_b64 exec, 0x2
	v_mov_b32_e32 v118, v37
	v_mov_b32_e32 v119, v36
	s_mov_b64 exec, 0x4
	v_mov_b32_e32 v118, v35
	v_mov_b32_e32 v119, v34
	s_mov_b64 exec, 0x8
	v_mov_b32_e32 v118, v33
	v_mov_b32_e32 v119, v32
	s_mov_b64 exec, 0x10
	v_mov_b32_e32 v118, v31
	v_mov_b32_e32 v119, v30
	s_mov_b64 exec, 0x20
	v_mov_b32_e32 v118, v29
	v_mov_b32_e32 v119, v28
	s_mov_b64 exec, 0x40
	v_mov_b32_e32 v118, v27
	v_mov_b32_e32 v119, v26
	s_mov_b64 exec, 0x80
	v_mov_b32_e32 v118, v25
	v_mov_b32_e32 v119, v24
	s_mov_b64 exec, 0x100
	v_mov_b32_e32 v118, v23
	v_mov_b32_e32 v119, v22
	s_mov_b64 exec, 0x200
	v_mov_b32_e32 v118, v21
	v_mov_b32_e32 v119, v20
	s_mov_b64 exec, 0x400
	v_mov_b32_e32 v118, v19
	v_mov_b32_e32 v119, v18
	s_mov_b64 exec, 0x800
	v_mov_b32_e32 v118, v17
	v_mov_b32_e32 v119, v16
	s_mov_b64 exec, 0x1000
	v_mov_b32_e32 v118, v15
	v_mov_b32_e32 v119, v14
	s_mov_b64 exec, 0x2000
	v_mov_b32_e32 v118, v13
	v_mov_b32_e32 v119, v12
	s_mov_b64 exec, 0x4000
	v_mov_b32_e32 v118, v11
	v_mov_b32_e32 v119, v10
	s_mov_b64 exec, 0x8000
	v_mov_b32_e32 v118, v9
	v_mov_b32_e32 v119, v8
	s_mov_b64 exec, 0x1111
	v_mov_b32_e32 v120, v7
	v_mov_b32_e32 v121, v114
	s_mov_b64 exec, 0x2222
	v_mov_b32_e32 v120, v111
	v_mov_b32_e32 v121, v115
	s_mov_b64 exec, 0x4444
	v_mov_b32_e32 v120, v112
	v_mov_b32_e32 v121, v116
	s_mov_b64 exec, 0x8888
	v_mov_b32_e32 v120, v113
	v_mov_b32_e32 v121, v117
	s_mov_b64 exec, 0xffff
	v_add_f32_e32 v122, v118, v120
	v_add_f32_e32 v39, v119, v121
	v_min_f32_e32 v38, 0, v39
	v_mul_f32_e64 v39, |v39|, s65
	v_exp_f32_e32 v39, v39
	s_nop 0
	v_add_f32_e32 v42, 1.0, v39
	v_add_f32_e32 v40, -1.0, v42
	v_sub_f32_e32 v41, v40, v42
	v_add_f32_e32 v41, 1.0, v41
	v_sub_f32_e32 v40, v39, v40
	v_add_f32_e32 v43, v40, v41
	v_frexp_mant_f32_e32 v40, v42
	v_cmp_gt_f32_e32 vcc, s4, v40
	v_cvt_f64_f32_e32 v[40:41], v42
	v_frexp_exp_i32_f64_e32 v40, v[40:41]
	v_subbrev_co_u32_e32 v40, vcc, 0, v40, vcc
	v_sub_u32_e32 v41, 0, v40
	v_ldexp_f32 v42, v42, v41
	v_ldexp_f32 v41, v43, v41
	v_add_f32_e32 v43, -1.0, v42
	v_add_f32_e32 v44, 1.0, v43
	v_sub_f32_e32 v44, v42, v44
	v_add_f32_e32 v44, v41, v44
	v_add_f32_e32 v45, v43, v44
	v_sub_f32_e32 v43, v45, v43
	v_sub_f32_e32 v43, v44, v43
	v_add_f32_e32 v44, 1.0, v42
	v_add_f32_e32 v46, -1.0, v44
	v_sub_f32_e32 v42, v42, v46
	v_add_f32_e32 v41, v41, v42
	v_add_f32_e32 v42, v44, v41
	v_sub_f32_e32 v44, v42, v44
	v_sub_f32_e32 v41, v41, v44
	v_rcp_f32_e32 v44, v42
	v_cvt_f32_i32_e32 v40, v40
	v_cmp_neq_f32_e32 vcc, s51, v39
	v_mul_f32_e32 v46, v45, v44
	v_mul_f32_e32 v47, v42, v46
	v_fma_f32 v48, v46, v42, -v47
	v_fmac_f32_e32 v48, v46, v41
	v_add_f32_e32 v49, v47, v48
	v_sub_f32_e32 v50, v45, v49
	v_sub_f32_e32 v45, v45, v50
	v_sub_f32_e32 v47, v49, v47
	v_sub_f32_e32 v45, v45, v49
	v_add_f32_e32 v43, v43, v45
	v_sub_f32_e32 v45, v47, v48
	v_add_f32_e32 v43, v45, v43
	v_add_f32_e32 v45, v50, v43
	v_mul_f32_e32 v47, v44, v45
	v_mul_f32_e32 v48, v42, v47
	v_fma_f32 v42, v47, v42, -v48
	v_fmac_f32_e32 v42, v47, v41
	v_sub_f32_e32 v41, v50, v45
	v_add_f32_e32 v41, v43, v41
	v_add_f32_e32 v43, v48, v42
	v_sub_f32_e32 v49, v45, v43
	v_sub_f32_e32 v45, v45, v49
	v_sub_f32_e32 v48, v43, v48
	v_sub_f32_e32 v43, v45, v43
	v_add_f32_e32 v41, v41, v43
	v_sub_f32_e32 v42, v48, v42
	v_add_f32_e32 v41, v42, v41
	v_add_f32_e32 v42, v46, v47
	v_add_f32_e32 v41, v49, v41
	v_sub_f32_e32 v43, v42, v46
	v_mul_f32_e32 v41, v44, v41
	v_sub_f32_e32 v43, v47, v43
	v_add_f32_e32 v41, v43, v41
	v_mul_f32_e32 v46, 0x3f317218, v40
	v_add_f32_e32 v43, v42, v41
	v_fma_f32 v47, v40, s5, -v46
	v_mul_f32_e32 v44, v43, v43
	v_fmac_f32_e32 v47, 0xb102e308, v40
	v_sub_f32_e32 v40, v43, v42
	v_fmamk_f32 v45, v44, 0x3e9b6dac, v226
	v_sub_f32_e32 v40, v41, v40
	v_add_f32_e32 v41, v46, v47
	v_fmaak_f32 v45, v44, v45, 0x3f2aaada
	v_sub_f32_e32 v42, v41, v46
	v_ldexp_f32 v46, v43, 1
	v_mul_f32_e32 v43, v43, v44
	v_mul_f32_e32 v43, v43, v45
	v_add_f32_e32 v44, v46, v43
	v_sub_f32_e32 v45, v44, v46
	v_ldexp_f32 v40, v40, 1
	v_sub_f32_e32 v43, v43, v45
	v_add_f32_e32 v40, v40, v43
	v_add_f32_e32 v43, v44, v40
	v_sub_f32_e32 v44, v43, v44
	v_sub_f32_e32 v40, v40, v44
	v_add_f32_e32 v44, v41, v43
	v_sub_f32_e32 v45, v44, v41
	v_sub_f32_e32 v46, v44, v45
	v_sub_f32_e32 v42, v47, v42
	v_sub_f32_e32 v41, v41, v46
	v_sub_f32_e32 v43, v43, v45
	v_add_f32_e32 v41, v43, v41
	v_add_f32_e32 v43, v42, v40
	v_sub_f32_e32 v45, v43, v42
	v_sub_f32_e32 v46, v43, v45
	v_sub_f32_e32 v42, v42, v46
	v_sub_f32_e32 v40, v40, v45
	v_add_f32_e32 v41, v43, v41
	v_add_f32_e32 v40, v40, v42
	v_add_f32_e32 v42, v44, v41
	v_sub_f32_e32 v43, v42, v44
	v_sub_f32_e32 v41, v41, v43
	v_add_f32_e32 v40, v40, v41
	v_add_f32_e32 v40, v42, v40
	v_cndmask_b32_e32 v40, v227, v40, vcc
	v_cmp_ngt_f32_e32 vcc, -1.0, v39
	s_nop 1
	v_cndmask_b32_e32 v40, v228, v40, vcc
	v_cmp_neq_f32_e32 vcc, -1.0, v39
	s_nop 1
	v_cndmask_b32_e32 v40, v229, v40, vcc
	v_cmp_lt_f32_e64 vcc, |v39|, s13
	s_nop 1
	v_cndmask_b32_e32 v39, v40, v39, vcc
	v_sub_f32_e32 v38, v38, v39
	v_lshrrev_b32_e32 v123, 2, v225
	v_and_b32_e32 v124, 3, v225
	v_lshlrev_b32_e32 v123, 5, v123
	v_lshl_or_b32 v123, v124, 2, v123
	global_store_dword v123, v122, s[0:1]
	global_store_dword v123, v38, s[0:1] offset:16
	s_branch .LBB0_322

; __device__ __forceinline__ void fox_unit(Frame& F, int h, int qb, int nrm_slot) {
;     ...
;     if (tid == 0) { const float* st = WSP(float, OFF_CTL) + 8192 + nrm_slot * 64 + h * 8; float r = 0.f;
; #pragma unroll
;         for (int sgi = 0; sgi < 8; ++sgi) { SP[sgi] = r; r += st[sgi]; } }
; __device__ __forceinline__ void mix_phase(Frame& F, int layer, int b, int pass) {
;     ...
;         if (F.tid == 0) *slot = (int)atomicAdd(cnt, 1u);
;         __syncthreads();
;         const int it = __builtin_amdgcn_readfirstlane(*slot);
;         __syncthreads();
;         if (it >= nscan + nfox) break;
;         if (it < nscan) {
;             if (pass == 0) { const int kind = it / (8 * (NGRP - 1)), rem = it % (8 * (NGRP - 1)), hv = rem / (NGRP - 1), grp = rem % (NGRP - 1);
;                 if (kind == 0) scan_unit<0, 0>(F, layer, hv >> 1, hv & 1, grp); else scan_unit<1, 0>(F, layer, hv >> 1, hv & 1, grp); }
;             else { const int kind = it / (8 * NGRP), hv = (it / NGRP) & 7, grp = it % NGRP;
;                 if (kind == 0) scan_unit<0, 1>(F, layer, hv >> 1, hv & 1, grp); else scan_unit<1, 1>(F, layer, hv >> 1, hv & 1, grp); }
;         } else { const int idx = fox0 + it - nscan; fox_unit(F, idx & 7, 31 - (idx >> 3), layer * NB + b); }
.LBB0_480:
	s_or_b64 exec, exec, s[0:1]
	v_readlane_b32 s0, v253, 35
	s_waitcnt lgkmcnt(0)
	s_barrier
	v_mov_b32_e32 v0, s0
	ds_read_b32 v0, v0
	s_mov_b64 s[0:1], -1
	s_waitcnt lgkmcnt(0)
	s_barrier
	v_readfirstlane_b32 s49, v0
	s_cmpk_gt_i32 s49, 0x1ff
	s_cbranch_scc1 .LBB0_477
	s_cmpk_gt_i32 s49, 0xff
	s_cbranch_scc0 .LBB0_512
	v_mov_b32_e32 v122, v154
	s_and_b32 s10, s49, 7
	s_nop 0
	v_readfirstlane_b32 s4, v122
	v_cmp_eq_u32_e32 vcc, 0, v122
	s_and_saveexec_b64 s[0:1], vcc
	s_cbranch_execz .LBB0_484
	s_lshl_b32 s5, s10, 5
	v_readlane_b32 s8, v254, 46
	s_add_u32 s8, s8, s5
	v_readlane_b32 s5, v254, 51
	s_addc_u32 s9, s5, 0
	ds_write_b32 v231, v1 offset:35072
	v_mov_b64_e32 v[2:3], s[8:9]
	global_load_dword v50, v[2:3], off
	global_load_dword v51, v[2:3], off offset:4
	global_load_dword v52, v[2:3], off offset:8
	global_load_dword v53, v[2:3], off offset:12
	global_load_dword v54, v[2:3], off offset:16
	global_load_dword v55, v[2:3], off offset:20
	global_load_dword v56, v[2:3], off offset:24
	s_waitcnt vmcnt(0)
	v_add_f32_e32 v0, 0, v50
	ds_write_b32 v231, v0 offset:35076
	v_add_f32_e32 v0, v0, v51
	ds_write_b32 v231, v0 offset:35080
	v_add_f32_e32 v0, v0, v52
	ds_write_b32 v231, v0 offset:35084
	v_add_f32_e32 v0, v0, v53
	ds_write_b32 v231, v0 offset:35088
	v_add_f32_e32 v0, v0, v54
	ds_write_b32 v231, v0 offset:35092
	v_add_f32_e32 v0, v0, v55
	ds_write_b32 v231, v0 offset:35096
	v_add_f32_e32 v0, v0, v56
	ds_write_b32 v231, v0 offset:35100
